# GEMM K-loops: serpentine MFMA order (all k0 sweeping m,n sharing one operand each step, then all k1 reversed); no accumulator chaining - comparison point
# baseline (speedup 1.0000x reference)
.LBB0_261:
	s_add_u32 s0, s76, 0xfff80080
	s_addc_u32 s1, s77, -1
	s_and_b64 s[84:85], s[84:85], exec
	s_cselect_b32 vcc_hi, s22, s1
	s_cselect_b32 vcc_lo, s23, s0
	s_cselect_b32 s85, s49, s58
	s_cselect_b32 s84, s57, s51
	s_add_i32 s0, 0, 0x10000
	s_add_i32 s1, 0, 0x14000
	v_add_u32_e32 v158, s0, v176
	v_add_u32_e32 v174, s1, v176
	ds_read_b128 v[146:149], v158
	ds_read_b128 v[150:153], v158 offset:1024
	ds_read_b128 v[154:157], v158 offset:2048
	ds_read_b128 v[158:161], v158 offset:3072
	ds_read_b128 v[162:165], v174
	ds_read_b128 v[166:169], v174 offset:1024
	ds_read_b128 v[170:173], v174 offset:2048
	ds_read_b128 v[178:181], v174 offset:3072
	v_lshl_add_u64 v[174:175], s[76:77], 0, v[138:139]
	s_add_i32 m0, s21, 0xc000
	ds_read_b128 v[182:185], v177
	ds_read_b128 v[186:189], v177 offset:1024
	ds_read_b128 v[190:193], v177 offset:2048
	ds_read_b128 v[204:207], v177 offset:3072
	ds_read_b128 v[208:211], v177 offset:4096
	ds_read_b128 v[212:215], v177 offset:5120
	ds_read_b128 v[216:219], v177 offset:6144
	ds_read_b128 v[220:223], v177 offset:7168
	global_load_lds_dwordx4 v[174:175], off
	v_lshl_add_u64 v[174:175], s[76:77], 0, v[140:141]
	s_add_i32 m0, s21, 0xe000
	s_nop 0
	global_load_lds_dwordx4 v[174:175], off
	s_waitcnt vmcnt(8)
	s_waitcnt lgkmcnt(0)
	s_barrier
	s_setprio 1
	s_waitcnt lgkmcnt(0)
	v_mfma_f32_16x16x32_bf16 v[126:129], v[146:149], v[182:185], v[126:129]
	v_mfma_f32_16x16x32_bf16 v[122:125], v[154:157], v[182:185], v[122:125]
	v_mfma_f32_16x16x32_bf16 v[118:121], v[162:165], v[182:185], v[118:121]
	v_mfma_f32_16x16x32_bf16 v[114:117], v[170:173], v[182:185], v[114:117]
	v_mfma_f32_16x16x32_bf16 v[98:101], v[170:173], v[190:193], v[98:101]
	v_mfma_f32_16x16x32_bf16 v[102:105], v[162:165], v[190:193], v[102:105]
	v_mfma_f32_16x16x32_bf16 v[106:109], v[154:157], v[190:193], v[106:109]
	v_mfma_f32_16x16x32_bf16 v[110:113], v[146:149], v[190:193], v[110:113]
	v_mfma_f32_16x16x32_bf16 v[94:97], v[146:149], v[208:211], v[94:97]
	v_mfma_f32_16x16x32_bf16 v[90:93], v[154:157], v[208:211], v[90:93]
	v_mfma_f32_16x16x32_bf16 v[86:89], v[162:165], v[208:211], v[86:89]
	v_mfma_f32_16x16x32_bf16 v[82:85], v[170:173], v[208:211], v[82:85]
	v_mfma_f32_16x16x32_bf16 v[66:69], v[170:173], v[216:219], v[66:69]
	v_mfma_f32_16x16x32_bf16 v[70:73], v[162:165], v[216:219], v[70:73]
	v_mfma_f32_16x16x32_bf16 v[74:77], v[154:157], v[216:219], v[74:77]
	v_mfma_f32_16x16x32_bf16 v[78:81], v[146:149], v[216:219], v[78:81]
	v_mfma_f32_16x16x32_bf16 v[78:81], v[150:153], v[220:223], v[78:81]
	v_mfma_f32_16x16x32_bf16 v[74:77], v[158:161], v[220:223], v[74:77]
	v_mfma_f32_16x16x32_bf16 v[70:73], v[166:169], v[220:223], v[70:73]
	v_mfma_f32_16x16x32_bf16 v[66:69], v[178:181], v[220:223], v[66:69]
	v_mfma_f32_16x16x32_bf16 v[82:85], v[178:181], v[212:215], v[82:85]
	v_mfma_f32_16x16x32_bf16 v[86:89], v[166:169], v[212:215], v[86:89]
	v_mfma_f32_16x16x32_bf16 v[90:93], v[158:161], v[212:215], v[90:93]
	v_mfma_f32_16x16x32_bf16 v[94:97], v[150:153], v[212:215], v[94:97]
	v_mfma_f32_16x16x32_bf16 v[110:113], v[150:153], v[204:207], v[110:113]
	v_mfma_f32_16x16x32_bf16 v[106:109], v[158:161], v[204:207], v[106:109]
	v_mfma_f32_16x16x32_bf16 v[102:105], v[166:169], v[204:207], v[102:105]
	v_mfma_f32_16x16x32_bf16 v[98:101], v[178:181], v[204:207], v[98:101]
	v_mfma_f32_16x16x32_bf16 v[114:117], v[178:181], v[186:189], v[114:117]
	v_mfma_f32_16x16x32_bf16 v[118:121], v[166:169], v[186:189], v[118:121]
	v_mfma_f32_16x16x32_bf16 v[122:125], v[158:161], v[186:189], v[122:125]
	v_mfma_f32_16x16x32_bf16 v[126:129], v[150:153], v[186:189], v[126:129]
	s_setprio 0
	s_barrier
	s_add_i32 s0, s0, s20
	v_lshl_add_u64 v[174:175], s[84:85], 0, v[132:133]
	s_mov_b32 m0, s0
	ds_read_b128 v[182:185], v177 offset:16384
	ds_read_b128 v[186:189], v177 offset:17408
	ds_read_b128 v[190:193], v177 offset:18432
	ds_read_b128 v[204:207], v177 offset:19456
	ds_read_b128 v[208:211], v177 offset:20480
	ds_read_b128 v[212:215], v177 offset:21504
	ds_read_b128 v[216:219], v177 offset:22528
	ds_read_b128 v[220:223], v177 offset:23552
	global_load_lds_dwordx4 v[174:175], off
	s_add_i32 m0, s0, 0x2000
	s_add_u32 s94, s84, 0x80000
	v_lshl_add_u64 v[224:225], s[84:85], 0, v[130:131]
	s_addc_u32 s95, s85, 0
	s_add_i32 s0, s1, s20
	global_load_lds_dwordx4 v[224:225], off
	v_lshl_add_u64 v[226:227], s[94:95], 0, v[132:133]
	s_mov_b32 m0, s0
	v_lshl_add_u64 v[228:229], vcc, 0, v[130:131]
	global_load_lds_dwordx4 v[226:227], off
	v_lshl_add_u64 v[226:227], s[94:95], 0, v[130:131]
	s_add_i32 m0, s0, 0x2000
	s_nop 0
	global_load_lds_dwordx4 v[226:227], off
	v_lshl_add_u64 v[226:227], vcc, 0, v[132:133]
	s_mov_b32 m0, s21
	s_nop 0
	global_load_lds_dwordx4 v[226:227], off
	s_mov_b32 m0, s26
	s_nop 0
	global_load_lds_dwordx4 v[228:229], off
	s_waitcnt vmcnt(8)
	s_waitcnt lgkmcnt(0)
	s_barrier
	s_setprio 1
	s_waitcnt lgkmcnt(0)
	v_mfma_f32_16x16x32_bf16 v[62:65], v[146:149], v[182:185], v[62:65]
	v_mfma_f32_16x16x32_bf16 v[58:61], v[154:157], v[182:185], v[58:61]
	v_mfma_f32_16x16x32_bf16 v[54:57], v[162:165], v[182:185], v[54:57]
	v_mfma_f32_16x16x32_bf16 v[50:53], v[170:173], v[182:185], v[50:53]
	v_mfma_f32_16x16x32_bf16 v[34:37], v[170:173], v[190:193], v[34:37]
	v_mfma_f32_16x16x32_bf16 v[38:41], v[162:165], v[190:193], v[38:41]
	v_mfma_f32_16x16x32_bf16 v[42:45], v[154:157], v[190:193], v[42:45]
	v_mfma_f32_16x16x32_bf16 v[46:49], v[146:149], v[190:193], v[46:49]
	v_mfma_f32_16x16x32_bf16 v[30:33], v[146:149], v[208:211], v[30:33]
	v_mfma_f32_16x16x32_bf16 v[26:29], v[154:157], v[208:211], v[26:29]
	v_mfma_f32_16x16x32_bf16 v[22:25], v[162:165], v[208:211], v[22:25]
	v_mfma_f32_16x16x32_bf16 v[18:21], v[170:173], v[208:211], v[18:21]
	v_mfma_f32_16x16x32_bf16 v[2:5], v[170:173], v[216:219], v[2:5]
	v_mfma_f32_16x16x32_bf16 v[6:9], v[162:165], v[216:219], v[6:9]
	v_mfma_f32_16x16x32_bf16 v[10:13], v[154:157], v[216:219], v[10:13]
	v_mfma_f32_16x16x32_bf16 v[14:17], v[146:149], v[216:219], v[14:17]
	v_mfma_f32_16x16x32_bf16 v[14:17], v[150:153], v[220:223], v[14:17]
	v_mfma_f32_16x16x32_bf16 v[10:13], v[158:161], v[220:223], v[10:13]
	v_mfma_f32_16x16x32_bf16 v[6:9], v[166:169], v[220:223], v[6:9]
	v_mfma_f32_16x16x32_bf16 v[2:5], v[178:181], v[220:223], v[2:5]
	v_mfma_f32_16x16x32_bf16 v[18:21], v[178:181], v[212:215], v[18:21]
	v_mfma_f32_16x16x32_bf16 v[22:25], v[166:169], v[212:215], v[22:25]
	v_mfma_f32_16x16x32_bf16 v[26:29], v[158:161], v[212:215], v[26:29]
	v_mfma_f32_16x16x32_bf16 v[30:33], v[150:153], v[212:215], v[30:33]
	v_mfma_f32_16x16x32_bf16 v[46:49], v[150:153], v[204:207], v[46:49]
	v_mfma_f32_16x16x32_bf16 v[42:45], v[158:161], v[204:207], v[42:45]
	v_mfma_f32_16x16x32_bf16 v[38:41], v[166:169], v[204:207], v[38:41]
	v_mfma_f32_16x16x32_bf16 v[34:37], v[178:181], v[204:207], v[34:37]
	v_mfma_f32_16x16x32_bf16 v[50:53], v[178:181], v[186:189], v[50:53]
	v_mfma_f32_16x16x32_bf16 v[54:57], v[166:169], v[186:189], v[54:57]
	v_mfma_f32_16x16x32_bf16 v[58:61], v[158:161], v[186:189], v[58:61]
	v_mfma_f32_16x16x32_bf16 v[62:65], v[150:153], v[186:189], v[62:65]
	s_setprio 0
	s_barrier
	s_add_i32 s0, 0, 0x18000
	s_add_i32 s1, 0, 0x1c000
	v_add_u32_e32 v158, s0, v176
	v_add_u32_e32 v178, s1, v176
	ds_read_b128 v[146:149], v158
	ds_read_b128 v[150:153], v158 offset:1024
	ds_read_b128 v[154:157], v158 offset:2048
	ds_read_b128 v[158:161], v158 offset:3072
	ds_read_b128 v[162:165], v178
	ds_read_b128 v[166:169], v178 offset:1024
	ds_read_b128 v[170:173], v178 offset:2048
	ds_read_b128 v[178:181], v178 offset:3072
	s_add_u32 s94, vcc_lo, 0x80000
	s_addc_u32 s95, vcc_hi, 0
	s_mov_b32 m0, s27
	v_lshl_add_u64 v[230:231], s[94:95], 0, v[132:133]
	ds_read_b128 v[182:185], v177 offset:32768
	ds_read_b128 v[186:189], v177 offset:33792
	ds_read_b128 v[190:193], v177 offset:34816
	ds_read_b128 v[204:207], v177 offset:35840
	ds_read_b128 v[208:211], v177 offset:36864
	ds_read_b128 v[212:215], v177 offset:37888
	ds_read_b128 v[216:219], v177 offset:38912
	ds_read_b128 v[220:223], v177 offset:39936
	global_load_lds_dwordx4 v[230:231], off
	v_lshl_add_u64 v[230:231], s[94:95], 0, v[130:131]
	s_mov_b32 m0, s29
	s_nop 0
	global_load_lds_dwordx4 v[230:231], off
	s_waitcnt vmcnt(8)
	s_waitcnt lgkmcnt(0)
	s_barrier
	s_setprio 1
	s_waitcnt lgkmcnt(0)
	v_mfma_f32_16x16x32_bf16 v[126:129], v[146:149], v[182:185], v[126:129]
	v_mfma_f32_16x16x32_bf16 v[122:125], v[154:157], v[182:185], v[122:125]
	v_mfma_f32_16x16x32_bf16 v[118:121], v[162:165], v[182:185], v[118:121]
	v_mfma_f32_16x16x32_bf16 v[114:117], v[170:173], v[182:185], v[114:117]
	v_mfma_f32_16x16x32_bf16 v[98:101], v[170:173], v[190:193], v[98:101]
	v_mfma_f32_16x16x32_bf16 v[102:105], v[162:165], v[190:193], v[102:105]
	v_mfma_f32_16x16x32_bf16 v[106:109], v[154:157], v[190:193], v[106:109]
	v_mfma_f32_16x16x32_bf16 v[110:113], v[146:149], v[190:193], v[110:113]
	v_mfma_f32_16x16x32_bf16 v[94:97], v[146:149], v[208:211], v[94:97]
	v_mfma_f32_16x16x32_bf16 v[90:93], v[154:157], v[208:211], v[90:93]
	v_mfma_f32_16x16x32_bf16 v[86:89], v[162:165], v[208:211], v[86:89]
	v_mfma_f32_16x16x32_bf16 v[82:85], v[170:173], v[208:211], v[82:85]
	v_mfma_f32_16x16x32_bf16 v[66:69], v[170:173], v[216:219], v[66:69]
	v_mfma_f32_16x16x32_bf16 v[70:73], v[162:165], v[216:219], v[70:73]
	v_mfma_f32_16x16x32_bf16 v[74:77], v[154:157], v[216:219], v[74:77]
	v_mfma_f32_16x16x32_bf16 v[78:81], v[146:149], v[216:219], v[78:81]
	v_mfma_f32_16x16x32_bf16 v[78:81], v[150:153], v[220:223], v[78:81]
	v_mfma_f32_16x16x32_bf16 v[74:77], v[158:161], v[220:223], v[74:77]
	v_mfma_f32_16x16x32_bf16 v[70:73], v[166:169], v[220:223], v[70:73]
	v_mfma_f32_16x16x32_bf16 v[66:69], v[178:181], v[220:223], v[66:69]
	v_mfma_f32_16x16x32_bf16 v[82:85], v[178:181], v[212:215], v[82:85]
	v_mfma_f32_16x16x32_bf16 v[86:89], v[166:169], v[212:215], v[86:89]
	v_mfma_f32_16x16x32_bf16 v[90:93], v[158:161], v[212:215], v[90:93]
	v_mfma_f32_16x16x32_bf16 v[94:97], v[150:153], v[212:215], v[94:97]
	v_mfma_f32_16x16x32_bf16 v[110:113], v[150:153], v[204:207], v[110:113]
	v_mfma_f32_16x16x32_bf16 v[106:109], v[158:161], v[204:207], v[106:109]
	v_mfma_f32_16x16x32_bf16 v[102:105], v[166:169], v[204:207], v[102:105]
	v_mfma_f32_16x16x32_bf16 v[98:101], v[178:181], v[204:207], v[98:101]
	v_mfma_f32_16x16x32_bf16 v[114:117], v[178:181], v[186:189], v[114:117]
	v_mfma_f32_16x16x32_bf16 v[118:121], v[166:169], v[186:189], v[118:121]
	v_mfma_f32_16x16x32_bf16 v[122:125], v[158:161], v[186:189], v[122:125]
	v_mfma_f32_16x16x32_bf16 v[126:129], v[150:153], v[186:189], v[126:129]
	s_setprio 0
	s_barrier
	s_add_i32 s0, s0, s20
	v_lshl_add_u64 v[174:175], v[174:175], 0, s[82:83]
	s_mov_b32 m0, s0
	ds_read_b128 v[182:185], v177 offset:49152
	ds_read_b128 v[186:189], v177 offset:50176
	ds_read_b128 v[190:193], v177 offset:51200
	ds_read_b128 v[204:207], v177 offset:52224
	ds_read_b128 v[208:211], v177 offset:53248
	ds_read_b128 v[212:215], v177 offset:54272
	ds_read_b128 v[216:219], v177 offset:55296
	ds_read_b128 v[220:223], v177 offset:56320
	global_load_lds_dwordx4 v[174:175], off
	s_add_i32 m0, s0, 0x2000
	s_add_u32 s84, s84, 0x80080
	v_lshl_add_u64 v[174:175], v[224:225], 0, s[82:83]
	s_addc_u32 s85, s85, 0
	s_add_i32 s0, s1, s20
	global_load_lds_dwordx4 v[174:175], off
	v_lshl_add_u64 v[174:175], s[84:85], 0, v[132:133]
	s_mov_b32 m0, s0
	s_nop 0
	global_load_lds_dwordx4 v[174:175], off
	v_lshl_add_u64 v[174:175], s[84:85], 0, v[130:131]
	s_add_i32 m0, s0, 0x2000
	s_nop 0
	global_load_lds_dwordx4 v[174:175], off
	v_lshl_add_u64 v[174:175], v[226:227], 0, s[82:83]
	s_mov_b32 m0, s40
	s_nop 0
	global_load_lds_dwordx4 v[174:175], off
	v_lshl_add_u64 v[174:175], v[228:229], 0, s[82:83]
	s_mov_b32 m0, s41
	s_nop 0
	global_load_lds_dwordx4 v[174:175], off
	s_waitcnt vmcnt(8)
	s_waitcnt lgkmcnt(0)
	s_barrier
	s_setprio 1
	s_waitcnt lgkmcnt(0)
	v_mfma_f32_16x16x32_bf16 v[62:65], v[146:149], v[182:185], v[62:65]
	v_mfma_f32_16x16x32_bf16 v[58:61], v[154:157], v[182:185], v[58:61]
	v_mfma_f32_16x16x32_bf16 v[54:57], v[162:165], v[182:185], v[54:57]
	v_mfma_f32_16x16x32_bf16 v[50:53], v[170:173], v[182:185], v[50:53]
	v_mfma_f32_16x16x32_bf16 v[34:37], v[170:173], v[190:193], v[34:37]
	v_mfma_f32_16x16x32_bf16 v[38:41], v[162:165], v[190:193], v[38:41]
	v_mfma_f32_16x16x32_bf16 v[42:45], v[154:157], v[190:193], v[42:45]
	v_mfma_f32_16x16x32_bf16 v[46:49], v[146:149], v[190:193], v[46:49]
	v_mfma_f32_16x16x32_bf16 v[30:33], v[146:149], v[208:211], v[30:33]
	v_mfma_f32_16x16x32_bf16 v[26:29], v[154:157], v[208:211], v[26:29]
	v_mfma_f32_16x16x32_bf16 v[22:25], v[162:165], v[208:211], v[22:25]
	v_mfma_f32_16x16x32_bf16 v[18:21], v[170:173], v[208:211], v[18:21]
	v_mfma_f32_16x16x32_bf16 v[2:5], v[170:173], v[216:219], v[2:5]
	v_mfma_f32_16x16x32_bf16 v[6:9], v[162:165], v[216:219], v[6:9]
	v_mfma_f32_16x16x32_bf16 v[10:13], v[154:157], v[216:219], v[10:13]
	v_mfma_f32_16x16x32_bf16 v[14:17], v[146:149], v[216:219], v[14:17]
	v_mfma_f32_16x16x32_bf16 v[14:17], v[150:153], v[220:223], v[14:17]
	v_mfma_f32_16x16x32_bf16 v[10:13], v[158:161], v[220:223], v[10:13]
	v_mfma_f32_16x16x32_bf16 v[6:9], v[166:169], v[220:223], v[6:9]
	v_mfma_f32_16x16x32_bf16 v[2:5], v[178:181], v[220:223], v[2:5]
	v_mfma_f32_16x16x32_bf16 v[18:21], v[178:181], v[212:215], v[18:21]
	v_mfma_f32_16x16x32_bf16 v[22:25], v[166:169], v[212:215], v[22:25]
	v_mfma_f32_16x16x32_bf16 v[26:29], v[158:161], v[212:215], v[26:29]
	v_mfma_f32_16x16x32_bf16 v[30:33], v[150:153], v[212:215], v[30:33]
	v_mfma_f32_16x16x32_bf16 v[46:49], v[150:153], v[204:207], v[46:49]
	v_mfma_f32_16x16x32_bf16 v[42:45], v[158:161], v[204:207], v[42:45]
	v_mfma_f32_16x16x32_bf16 v[38:41], v[166:169], v[204:207], v[38:41]
	v_mfma_f32_16x16x32_bf16 v[34:37], v[178:181], v[204:207], v[34:37]
	v_mfma_f32_16x16x32_bf16 v[50:53], v[178:181], v[186:189], v[50:53]
	v_mfma_f32_16x16x32_bf16 v[54:57], v[166:169], v[186:189], v[54:57]
	v_mfma_f32_16x16x32_bf16 v[58:61], v[158:161], v[186:189], v[58:61]
	v_mfma_f32_16x16x32_bf16 v[62:65], v[150:153], v[186:189], v[62:65]
	s_setprio 0
	s_barrier
	s_add_i32 s65, s65, 2
	s_add_u32 s76, s76, 0x100
	s_addc_u32 s77, s77, 0
	s_add_u32 s51, s51, 0x100
	s_addc_u32 s58, s58, 0
	s_cmp_gt_u32 s65, 29
	s_cbranch_scc1 .LBB0_264

.LBB0_285:
	s_add_u32 s0, s76, 0xfff80080
	s_addc_u32 s1, s77, -1
	s_and_b64 s[70:71], s[70:71], exec
	s_cselect_b32 vcc_hi, s21, s1
	s_cselect_b32 vcc_lo, s22, s0
	s_cselect_b32 s71, s23, s41
	s_cselect_b32 s70, s39, s7
	s_add_i32 s0, 0, 0x10000
	s_add_i32 s1, 0, 0x14000
	v_add_u32_e32 v146, s0, v1
	v_add_u32_e32 v174, s1, v1
	ds_read_b128 v[134:137], v146
	ds_read_b128 v[138:141], v146 offset:1024
	ds_read_b128 v[142:145], v146 offset:2048
	ds_read_b128 v[146:149], v146 offset:3072
	ds_read_b128 v[150:153], v174
	ds_read_b128 v[154:157], v174 offset:1024
	ds_read_b128 v[158:161], v174 offset:2048
	ds_read_b128 v[174:177], v174 offset:3072
	v_lshl_add_u64 v[220:221], s[76:77], 0, v[170:171]
	s_add_i32 m0, s67, 0xc000
	ds_read_b128 v[178:181], v222
	ds_read_b128 v[182:185], v222 offset:1024
	ds_read_b128 v[186:189], v222 offset:2048
	ds_read_b128 v[190:193], v222 offset:3072
	ds_read_b128 v[204:207], v222 offset:4096
	ds_read_b128 v[208:211], v222 offset:5120
	ds_read_b128 v[212:215], v222 offset:6144
	ds_read_b128 v[216:219], v222 offset:7168
	global_load_lds_dwordx4 v[220:221], off
	v_lshl_add_u64 v[220:221], s[76:77], 0, v[172:173]
	s_add_i32 m0, s67, 0xe000
	s_nop 0
	global_load_lds_dwordx4 v[220:221], off
	s_waitcnt vmcnt(8)
	s_waitcnt lgkmcnt(0)
	s_barrier
	s_setprio 1
	s_waitcnt lgkmcnt(0)
	v_mfma_f32_16x16x32_bf16 v[126:129], v[134:137], v[178:181], v[126:129]
	v_mfma_f32_16x16x32_bf16 v[122:125], v[142:145], v[178:181], v[122:125]
	v_mfma_f32_16x16x32_bf16 v[118:121], v[150:153], v[178:181], v[118:121]
	v_mfma_f32_16x16x32_bf16 v[114:117], v[158:161], v[178:181], v[114:117]
	v_mfma_f32_16x16x32_bf16 v[98:101], v[158:161], v[186:189], v[98:101]
	v_mfma_f32_16x16x32_bf16 v[102:105], v[150:153], v[186:189], v[102:105]
	v_mfma_f32_16x16x32_bf16 v[106:109], v[142:145], v[186:189], v[106:109]
	v_mfma_f32_16x16x32_bf16 v[110:113], v[134:137], v[186:189], v[110:113]
	v_mfma_f32_16x16x32_bf16 v[94:97], v[134:137], v[204:207], v[94:97]
	v_mfma_f32_16x16x32_bf16 v[90:93], v[142:145], v[204:207], v[90:93]
	v_mfma_f32_16x16x32_bf16 v[86:89], v[150:153], v[204:207], v[86:89]
	v_mfma_f32_16x16x32_bf16 v[82:85], v[158:161], v[204:207], v[82:85]
	v_mfma_f32_16x16x32_bf16 v[66:69], v[158:161], v[212:215], v[66:69]
	v_mfma_f32_16x16x32_bf16 v[70:73], v[150:153], v[212:215], v[70:73]
	v_mfma_f32_16x16x32_bf16 v[74:77], v[142:145], v[212:215], v[74:77]
	v_mfma_f32_16x16x32_bf16 v[78:81], v[134:137], v[212:215], v[78:81]
	v_mfma_f32_16x16x32_bf16 v[78:81], v[138:141], v[216:219], v[78:81]
	v_mfma_f32_16x16x32_bf16 v[74:77], v[146:149], v[216:219], v[74:77]
	v_mfma_f32_16x16x32_bf16 v[70:73], v[154:157], v[216:219], v[70:73]
	v_mfma_f32_16x16x32_bf16 v[66:69], v[174:177], v[216:219], v[66:69]
	v_mfma_f32_16x16x32_bf16 v[82:85], v[174:177], v[208:211], v[82:85]
	v_mfma_f32_16x16x32_bf16 v[86:89], v[154:157], v[208:211], v[86:89]
	v_mfma_f32_16x16x32_bf16 v[90:93], v[146:149], v[208:211], v[90:93]
	v_mfma_f32_16x16x32_bf16 v[94:97], v[138:141], v[208:211], v[94:97]
	v_mfma_f32_16x16x32_bf16 v[110:113], v[138:141], v[190:193], v[110:113]
	v_mfma_f32_16x16x32_bf16 v[106:109], v[146:149], v[190:193], v[106:109]
	v_mfma_f32_16x16x32_bf16 v[102:105], v[154:157], v[190:193], v[102:105]
	v_mfma_f32_16x16x32_bf16 v[98:101], v[174:177], v[190:193], v[98:101]
	v_mfma_f32_16x16x32_bf16 v[114:117], v[174:177], v[182:185], v[114:117]
	v_mfma_f32_16x16x32_bf16 v[118:121], v[154:157], v[182:185], v[118:121]
	v_mfma_f32_16x16x32_bf16 v[122:125], v[146:149], v[182:185], v[122:125]
	v_mfma_f32_16x16x32_bf16 v[126:129], v[138:141], v[182:185], v[126:129]
	s_setprio 0
	s_barrier
	s_add_i32 s0, s0, s54
	v_lshl_add_u64 v[220:221], s[70:71], 0, v[164:165]
	s_mov_b32 m0, s0
	ds_read_b128 v[178:181], v222 offset:16384
	ds_read_b128 v[182:185], v222 offset:17408
	ds_read_b128 v[186:189], v222 offset:18432
	ds_read_b128 v[190:193], v222 offset:19456
	ds_read_b128 v[204:207], v222 offset:20480
	ds_read_b128 v[208:211], v222 offset:21504
	ds_read_b128 v[212:215], v222 offset:22528
	ds_read_b128 v[216:219], v222 offset:23552
	global_load_lds_dwordx4 v[220:221], off
	s_add_i32 m0, s0, 0x2000
	s_add_u32 s44, s70, 0x80000
	v_lshl_add_u64 v[224:225], s[70:71], 0, v[162:163]
	s_addc_u32 s45, s71, 0
	s_add_i32 s0, s1, s54
	global_load_lds_dwordx4 v[224:225], off
	v_lshl_add_u64 v[226:227], s[44:45], 0, v[164:165]
	s_mov_b32 m0, s0
	v_lshl_add_u64 v[228:229], vcc, 0, v[162:163]
	global_load_lds_dwordx4 v[226:227], off
	v_lshl_add_u64 v[226:227], s[44:45], 0, v[162:163]
	s_add_i32 m0, s0, 0x2000
	s_nop 0
	global_load_lds_dwordx4 v[226:227], off
	v_lshl_add_u64 v[226:227], vcc, 0, v[164:165]
	s_mov_b32 m0, s67
	s_nop 0
	global_load_lds_dwordx4 v[226:227], off
	s_mov_b32 m0, s68
	s_nop 0
	global_load_lds_dwordx4 v[228:229], off
	s_waitcnt vmcnt(8)
	s_waitcnt lgkmcnt(0)
	s_barrier
	s_setprio 1
	s_waitcnt lgkmcnt(0)
	v_mfma_f32_16x16x32_bf16 v[62:65], v[134:137], v[178:181], v[62:65]
	v_mfma_f32_16x16x32_bf16 v[58:61], v[142:145], v[178:181], v[58:61]
	v_mfma_f32_16x16x32_bf16 v[54:57], v[150:153], v[178:181], v[54:57]
	v_mfma_f32_16x16x32_bf16 v[50:53], v[158:161], v[178:181], v[50:53]
	v_mfma_f32_16x16x32_bf16 v[34:37], v[158:161], v[186:189], v[34:37]
	v_mfma_f32_16x16x32_bf16 v[38:41], v[150:153], v[186:189], v[38:41]
	v_mfma_f32_16x16x32_bf16 v[42:45], v[142:145], v[186:189], v[42:45]
	v_mfma_f32_16x16x32_bf16 v[46:49], v[134:137], v[186:189], v[46:49]
	v_mfma_f32_16x16x32_bf16 v[30:33], v[134:137], v[204:207], v[30:33]
	v_mfma_f32_16x16x32_bf16 v[26:29], v[142:145], v[204:207], v[26:29]
	v_mfma_f32_16x16x32_bf16 v[22:25], v[150:153], v[204:207], v[22:25]
	v_mfma_f32_16x16x32_bf16 v[18:21], v[158:161], v[204:207], v[18:21]
	v_mfma_f32_16x16x32_bf16 v[2:5], v[158:161], v[212:215], v[2:5]
	v_mfma_f32_16x16x32_bf16 v[6:9], v[150:153], v[212:215], v[6:9]
	v_mfma_f32_16x16x32_bf16 v[10:13], v[142:145], v[212:215], v[10:13]
	v_mfma_f32_16x16x32_bf16 v[14:17], v[134:137], v[212:215], v[14:17]
	v_mfma_f32_16x16x32_bf16 v[14:17], v[138:141], v[216:219], v[14:17]
	v_mfma_f32_16x16x32_bf16 v[10:13], v[146:149], v[216:219], v[10:13]
	v_mfma_f32_16x16x32_bf16 v[6:9], v[154:157], v[216:219], v[6:9]
	v_mfma_f32_16x16x32_bf16 v[2:5], v[174:177], v[216:219], v[2:5]
	v_mfma_f32_16x16x32_bf16 v[18:21], v[174:177], v[208:211], v[18:21]
	v_mfma_f32_16x16x32_bf16 v[22:25], v[154:157], v[208:211], v[22:25]
	v_mfma_f32_16x16x32_bf16 v[26:29], v[146:149], v[208:211], v[26:29]
	v_mfma_f32_16x16x32_bf16 v[30:33], v[138:141], v[208:211], v[30:33]
	v_mfma_f32_16x16x32_bf16 v[46:49], v[138:141], v[190:193], v[46:49]
	v_mfma_f32_16x16x32_bf16 v[42:45], v[146:149], v[190:193], v[42:45]
	v_mfma_f32_16x16x32_bf16 v[38:41], v[154:157], v[190:193], v[38:41]
	v_mfma_f32_16x16x32_bf16 v[34:37], v[174:177], v[190:193], v[34:37]
	v_mfma_f32_16x16x32_bf16 v[50:53], v[174:177], v[182:185], v[50:53]
	v_mfma_f32_16x16x32_bf16 v[54:57], v[154:157], v[182:185], v[54:57]
	v_mfma_f32_16x16x32_bf16 v[58:61], v[146:149], v[182:185], v[58:61]
	v_mfma_f32_16x16x32_bf16 v[62:65], v[138:141], v[182:185], v[62:65]
	s_setprio 0
	s_barrier
	s_add_i32 s0, 0, 0x18000
	s_add_i32 s1, 0, 0x1c000
	v_add_u32_e32 v146, s0, v1
	v_add_u32_e32 v174, s1, v1
	ds_read_b128 v[134:137], v146
	ds_read_b128 v[138:141], v146 offset:1024
	ds_read_b128 v[142:145], v146 offset:2048
	ds_read_b128 v[146:149], v146 offset:3072
	ds_read_b128 v[150:153], v174
	ds_read_b128 v[154:157], v174 offset:1024
	ds_read_b128 v[158:161], v174 offset:2048
	ds_read_b128 v[174:177], v174 offset:3072
	s_add_u32 s44, vcc_lo, 0x80000
	s_addc_u32 s45, vcc_hi, 0
	s_mov_b32 m0, s8
	v_lshl_add_u64 v[230:231], s[44:45], 0, v[164:165]
	ds_read_b128 v[178:181], v222 offset:32768
	ds_read_b128 v[182:185], v222 offset:33792
	ds_read_b128 v[186:189], v222 offset:34816
	ds_read_b128 v[190:193], v222 offset:35840
	ds_read_b128 v[204:207], v222 offset:36864
	ds_read_b128 v[208:211], v222 offset:37888
	ds_read_b128 v[212:215], v222 offset:38912
	ds_read_b128 v[216:219], v222 offset:39936
	global_load_lds_dwordx4 v[230:231], off
	v_lshl_add_u64 v[230:231], s[44:45], 0, v[162:163]
	s_mov_b32 m0, s9
	s_nop 0
	global_load_lds_dwordx4 v[230:231], off
	s_waitcnt vmcnt(8)
	s_waitcnt lgkmcnt(0)
	s_barrier
	s_setprio 1
	s_waitcnt lgkmcnt(0)
	v_mfma_f32_16x16x32_bf16 v[126:129], v[134:137], v[178:181], v[126:129]
	v_mfma_f32_16x16x32_bf16 v[122:125], v[142:145], v[178:181], v[122:125]
	v_mfma_f32_16x16x32_bf16 v[118:121], v[150:153], v[178:181], v[118:121]
	v_mfma_f32_16x16x32_bf16 v[114:117], v[158:161], v[178:181], v[114:117]
	v_mfma_f32_16x16x32_bf16 v[98:101], v[158:161], v[186:189], v[98:101]
	v_mfma_f32_16x16x32_bf16 v[102:105], v[150:153], v[186:189], v[102:105]
	v_mfma_f32_16x16x32_bf16 v[106:109], v[142:145], v[186:189], v[106:109]
	v_mfma_f32_16x16x32_bf16 v[110:113], v[134:137], v[186:189], v[110:113]
	v_mfma_f32_16x16x32_bf16 v[94:97], v[134:137], v[204:207], v[94:97]
	v_mfma_f32_16x16x32_bf16 v[90:93], v[142:145], v[204:207], v[90:93]
	v_mfma_f32_16x16x32_bf16 v[86:89], v[150:153], v[204:207], v[86:89]
	v_mfma_f32_16x16x32_bf16 v[82:85], v[158:161], v[204:207], v[82:85]
	v_mfma_f32_16x16x32_bf16 v[66:69], v[158:161], v[212:215], v[66:69]
	v_mfma_f32_16x16x32_bf16 v[70:73], v[150:153], v[212:215], v[70:73]
	v_mfma_f32_16x16x32_bf16 v[74:77], v[142:145], v[212:215], v[74:77]
	v_mfma_f32_16x16x32_bf16 v[78:81], v[134:137], v[212:215], v[78:81]
	v_mfma_f32_16x16x32_bf16 v[78:81], v[138:141], v[216:219], v[78:81]
	v_mfma_f32_16x16x32_bf16 v[74:77], v[146:149], v[216:219], v[74:77]
	v_mfma_f32_16x16x32_bf16 v[70:73], v[154:157], v[216:219], v[70:73]
	v_mfma_f32_16x16x32_bf16 v[66:69], v[174:177], v[216:219], v[66:69]
	v_mfma_f32_16x16x32_bf16 v[82:85], v[174:177], v[208:211], v[82:85]
	v_mfma_f32_16x16x32_bf16 v[86:89], v[154:157], v[208:211], v[86:89]
	v_mfma_f32_16x16x32_bf16 v[90:93], v[146:149], v[208:211], v[90:93]
	v_mfma_f32_16x16x32_bf16 v[94:97], v[138:141], v[208:211], v[94:97]
	v_mfma_f32_16x16x32_bf16 v[110:113], v[138:141], v[190:193], v[110:113]
	v_mfma_f32_16x16x32_bf16 v[106:109], v[146:149], v[190:193], v[106:109]
	v_mfma_f32_16x16x32_bf16 v[102:105], v[154:157], v[190:193], v[102:105]
	v_mfma_f32_16x16x32_bf16 v[98:101], v[174:177], v[190:193], v[98:101]
	v_mfma_f32_16x16x32_bf16 v[114:117], v[174:177], v[182:185], v[114:117]
	v_mfma_f32_16x16x32_bf16 v[118:121], v[154:157], v[182:185], v[118:121]
	v_mfma_f32_16x16x32_bf16 v[122:125], v[146:149], v[182:185], v[122:125]
	v_mfma_f32_16x16x32_bf16 v[126:129], v[138:141], v[182:185], v[126:129]
	s_setprio 0
	s_barrier
	s_add_i32 s0, s0, s54
	v_lshl_add_u64 v[220:221], v[220:221], 0, s[82:83]
	s_mov_b32 m0, s0
	ds_read_b128 v[178:181], v222 offset:49152
	ds_read_b128 v[182:185], v222 offset:50176
	ds_read_b128 v[186:189], v222 offset:51200
	ds_read_b128 v[190:193], v222 offset:52224
	ds_read_b128 v[204:207], v222 offset:53248
	ds_read_b128 v[208:211], v222 offset:54272
	ds_read_b128 v[212:215], v222 offset:55296
	ds_read_b128 v[216:219], v222 offset:56320
	global_load_lds_dwordx4 v[220:221], off
	s_add_i32 m0, s0, 0x2000
	s_add_u32 s44, s70, 0x80080
	v_lshl_add_u64 v[220:221], v[224:225], 0, s[82:83]
	s_addc_u32 s45, s71, 0
	s_add_i32 s0, s1, s54
	global_load_lds_dwordx4 v[220:221], off
	v_lshl_add_u64 v[220:221], s[44:45], 0, v[164:165]
	s_mov_b32 m0, s0
	s_nop 0
	global_load_lds_dwordx4 v[220:221], off
	v_lshl_add_u64 v[220:221], s[44:45], 0, v[162:163]
	s_add_i32 m0, s0, 0x2000
	s_nop 0
	global_load_lds_dwordx4 v[220:221], off
	v_lshl_add_u64 v[220:221], v[226:227], 0, s[82:83]
	s_mov_b32 m0, s27
	s_nop 0
	global_load_lds_dwordx4 v[220:221], off
	v_lshl_add_u64 v[220:221], v[228:229], 0, s[82:83]
	s_mov_b32 m0, s26
	s_nop 0
	global_load_lds_dwordx4 v[220:221], off
	s_waitcnt vmcnt(8)
	s_waitcnt lgkmcnt(0)
	s_barrier
	s_setprio 1
	s_waitcnt lgkmcnt(0)
	v_mfma_f32_16x16x32_bf16 v[62:65], v[134:137], v[178:181], v[62:65]
	v_mfma_f32_16x16x32_bf16 v[58:61], v[142:145], v[178:181], v[58:61]
	v_mfma_f32_16x16x32_bf16 v[54:57], v[150:153], v[178:181], v[54:57]
	v_mfma_f32_16x16x32_bf16 v[50:53], v[158:161], v[178:181], v[50:53]
	v_mfma_f32_16x16x32_bf16 v[34:37], v[158:161], v[186:189], v[34:37]
	v_mfma_f32_16x16x32_bf16 v[38:41], v[150:153], v[186:189], v[38:41]
	v_mfma_f32_16x16x32_bf16 v[42:45], v[142:145], v[186:189], v[42:45]
	v_mfma_f32_16x16x32_bf16 v[46:49], v[134:137], v[186:189], v[46:49]
	v_mfma_f32_16x16x32_bf16 v[30:33], v[134:137], v[204:207], v[30:33]
	v_mfma_f32_16x16x32_bf16 v[26:29], v[142:145], v[204:207], v[26:29]
	v_mfma_f32_16x16x32_bf16 v[22:25], v[150:153], v[204:207], v[22:25]
	v_mfma_f32_16x16x32_bf16 v[18:21], v[158:161], v[204:207], v[18:21]
	v_mfma_f32_16x16x32_bf16 v[2:5], v[158:161], v[212:215], v[2:5]
	v_mfma_f32_16x16x32_bf16 v[6:9], v[150:153], v[212:215], v[6:9]
	v_mfma_f32_16x16x32_bf16 v[10:13], v[142:145], v[212:215], v[10:13]
	v_mfma_f32_16x16x32_bf16 v[14:17], v[134:137], v[212:215], v[14:17]
	v_mfma_f32_16x16x32_bf16 v[14:17], v[138:141], v[216:219], v[14:17]
	v_mfma_f32_16x16x32_bf16 v[10:13], v[146:149], v[216:219], v[10:13]
	v_mfma_f32_16x16x32_bf16 v[6:9], v[154:157], v[216:219], v[6:9]
	v_mfma_f32_16x16x32_bf16 v[2:5], v[174:177], v[216:219], v[2:5]
	v_mfma_f32_16x16x32_bf16 v[18:21], v[174:177], v[208:211], v[18:21]
	v_mfma_f32_16x16x32_bf16 v[22:25], v[154:157], v[208:211], v[22:25]
	v_mfma_f32_16x16x32_bf16 v[26:29], v[146:149], v[208:211], v[26:29]
	v_mfma_f32_16x16x32_bf16 v[30:33], v[138:141], v[208:211], v[30:33]
	v_mfma_f32_16x16x32_bf16 v[46:49], v[138:141], v[190:193], v[46:49]
	v_mfma_f32_16x16x32_bf16 v[42:45], v[146:149], v[190:193], v[42:45]
	v_mfma_f32_16x16x32_bf16 v[38:41], v[154:157], v[190:193], v[38:41]
	v_mfma_f32_16x16x32_bf16 v[34:37], v[174:177], v[190:193], v[34:37]
	v_mfma_f32_16x16x32_bf16 v[50:53], v[174:177], v[182:185], v[50:53]
	v_mfma_f32_16x16x32_bf16 v[54:57], v[154:157], v[182:185], v[54:57]
	v_mfma_f32_16x16x32_bf16 v[58:61], v[146:149], v[182:185], v[58:61]
	v_mfma_f32_16x16x32_bf16 v[62:65], v[138:141], v[182:185], v[62:65]
	s_setprio 0
	s_barrier
	s_add_i32 s43, s43, 2
	s_add_u32 s76, s76, 0x100
	s_addc_u32 s77, s77, 0
	s_add_u32 s7, s7, 0x100
	s_addc_u32 s41, s41, 0
	s_cmp_gt_u32 s43, 29
	s_cbranch_scc1 .LBB0_288

.LBB0_509:
	s_add_u32 s90, s76, 0x100
	s_addc_u32 s91, s77, 0
	s_and_b64 s[0:1], s[70:71], exec
	s_cselect_b32 vcc_hi, s22, s91
	s_cselect_b32 vcc_lo, s23, s90
	s_cselect_b32 s71, s41, s53
	s_cselect_b32 s70, s44, s51
	s_add_i32 s0, 0, 0x10000
	s_add_i32 s18, 0, 0x14000
	v_add_u32_e32 v114, s0, v1
	v_add_u32_e32 v154, s18, v1
	ds_read_b128 v[78:81], v114
	ds_read_b128 v[90:93], v114 offset:1024
	ds_read_b128 v[102:105], v114 offset:2048
	ds_read_b128 v[114:117], v114 offset:3072
	ds_read_b128 v[126:129], v154
	ds_read_b128 v[134:137], v154 offset:1024
	ds_read_b128 v[142:145], v154 offset:2048
	ds_read_b128 v[154:157], v154 offset:3072
	v_lshl_add_u64 v[218:219], s[76:77], 0, v[210:211]
	s_add_i32 m0, s29, 0xc000
	ds_read_b128 v[158:161], v237
	ds_read_b128 v[162:165], v237 offset:1024
	ds_read_b128 v[166:169], v237 offset:2048
	ds_read_b128 v[178:181], v237 offset:3072
	ds_read_b128 v[182:185], v237 offset:4096
	ds_read_b128 v[186:189], v237 offset:5120
	ds_read_b128 v[190:193], v237 offset:6144
	ds_read_b128 v[214:217], v237 offset:7168
	global_load_lds_dwordx4 v[218:219], off
	v_lshl_add_u64 v[218:219], s[76:77], 0, v[212:213]
	s_add_i32 m0, s29, 0xe000
	s_nop 0
	global_load_lds_dwordx4 v[218:219], off
	s_waitcnt vmcnt(8)
	s_waitcnt lgkmcnt(0)
	s_barrier
	s_setprio 1
	s_waitcnt lgkmcnt(0)
	v_mfma_f32_16x16x32_bf16 v[174:177], v[78:81], v[158:161], v[174:177]
	v_mfma_f32_16x16x32_bf16 v[170:173], v[102:105], v[158:161], v[170:173]
	v_mfma_f32_16x16x32_bf16 v[150:153], v[126:129], v[158:161], v[150:153]
	v_mfma_f32_16x16x32_bf16 v[146:149], v[142:145], v[158:161], v[146:149]
	v_mfma_f32_16x16x32_bf16 v[118:121], v[142:145], v[166:169], v[118:121]
	v_mfma_f32_16x16x32_bf16 v[122:125], v[126:129], v[166:169], v[122:125]
	v_mfma_f32_16x16x32_bf16 v[130:133], v[102:105], v[166:169], v[130:133]
	v_mfma_f32_16x16x32_bf16 v[138:141], v[78:81], v[166:169], v[138:141]
	v_mfma_f32_16x16x32_bf16 v[110:113], v[78:81], v[182:185], v[110:113]
	v_mfma_f32_16x16x32_bf16 v[106:109], v[102:105], v[182:185], v[106:109]
	v_mfma_f32_16x16x32_bf16 v[98:101], v[126:129], v[182:185], v[98:101]
	v_mfma_f32_16x16x32_bf16 v[94:97], v[142:145], v[182:185], v[94:97]
	v_mfma_f32_16x16x32_bf16 v[66:69], v[142:145], v[190:193], v[66:69]
	v_mfma_f32_16x16x32_bf16 v[74:77], v[126:129], v[190:193], v[74:77]
	v_mfma_f32_16x16x32_bf16 v[82:85], v[102:105], v[190:193], v[82:85]
	v_mfma_f32_16x16x32_bf16 v[86:89], v[78:81], v[190:193], v[86:89]
	v_mfma_f32_16x16x32_bf16 v[86:89], v[90:93], v[214:217], v[86:89]
	v_mfma_f32_16x16x32_bf16 v[82:85], v[114:117], v[214:217], v[82:85]
	v_mfma_f32_16x16x32_bf16 v[74:77], v[134:137], v[214:217], v[74:77]
	v_mfma_f32_16x16x32_bf16 v[66:69], v[154:157], v[214:217], v[66:69]
	v_mfma_f32_16x16x32_bf16 v[94:97], v[154:157], v[186:189], v[94:97]
	v_mfma_f32_16x16x32_bf16 v[98:101], v[134:137], v[186:189], v[98:101]
	v_mfma_f32_16x16x32_bf16 v[106:109], v[114:117], v[186:189], v[106:109]
	v_mfma_f32_16x16x32_bf16 v[110:113], v[90:93], v[186:189], v[110:113]
	v_mfma_f32_16x16x32_bf16 v[138:141], v[90:93], v[178:181], v[138:141]
	v_mfma_f32_16x16x32_bf16 v[130:133], v[114:117], v[178:181], v[130:133]
	v_mfma_f32_16x16x32_bf16 v[122:125], v[134:137], v[178:181], v[122:125]
	v_mfma_f32_16x16x32_bf16 v[118:121], v[154:157], v[178:181], v[118:121]
	v_mfma_f32_16x16x32_bf16 v[146:149], v[154:157], v[162:165], v[146:149]
	v_mfma_f32_16x16x32_bf16 v[150:153], v[134:137], v[162:165], v[150:153]
	v_mfma_f32_16x16x32_bf16 v[170:173], v[114:117], v[162:165], v[170:173]
	v_mfma_f32_16x16x32_bf16 v[174:177], v[90:93], v[162:165], v[174:177]
	s_setprio 0
	s_barrier
	s_add_i32 s0, s0, s28
	v_lshl_add_u64 v[218:219], s[70:71], 0, v[194:195]
	s_mov_b32 m0, s0
	ds_read_b128 v[158:161], v237 offset:16384
	ds_read_b128 v[162:165], v237 offset:17408
	ds_read_b128 v[166:169], v237 offset:18432
	ds_read_b128 v[178:181], v237 offset:19456
	ds_read_b128 v[182:185], v237 offset:20480
	ds_read_b128 v[186:189], v237 offset:21504
	ds_read_b128 v[190:193], v237 offset:22528
	ds_read_b128 v[214:217], v237 offset:23552
	global_load_lds_dwordx4 v[218:219], off
	s_add_i32 m0, s0, 0x2000
	s_add_u32 s0, s70, 0x80000
	v_lshl_add_u64 v[220:221], s[70:71], 0, v[204:205]
	s_addc_u32 s1, s71, 0
	s_add_i32 s18, s18, s28
	global_load_lds_dwordx4 v[220:221], off
	v_lshl_add_u64 v[222:223], s[0:1], 0, v[194:195]
	s_mov_b32 m0, s18
	v_lshl_add_u64 v[224:225], vcc, 0, v[204:205]
	global_load_lds_dwordx4 v[222:223], off
	v_lshl_add_u64 v[222:223], s[0:1], 0, v[204:205]
	s_add_i32 m0, s18, 0x2000
	s_nop 0
	global_load_lds_dwordx4 v[222:223], off
	v_lshl_add_u64 v[222:223], vcc, 0, v[194:195]
	s_mov_b32 m0, s29
	s_nop 0
	global_load_lds_dwordx4 v[222:223], off
	s_mov_b32 m0, s31
	s_nop 0
	global_load_lds_dwordx4 v[224:225], off
	s_waitcnt vmcnt(8)
	s_waitcnt lgkmcnt(0)
	s_barrier
	s_setprio 1
	s_waitcnt lgkmcnt(0)
	v_mfma_f32_16x16x32_bf16 v[62:65], v[78:81], v[158:161], v[62:65]
	v_mfma_f32_16x16x32_bf16 v[58:61], v[102:105], v[158:161], v[58:61]
	v_mfma_f32_16x16x32_bf16 v[54:57], v[126:129], v[158:161], v[54:57]
	v_mfma_f32_16x16x32_bf16 v[50:53], v[142:145], v[158:161], v[50:53]
	v_mfma_f32_16x16x32_bf16 v[34:37], v[142:145], v[166:169], v[34:37]
	v_mfma_f32_16x16x32_bf16 v[38:41], v[126:129], v[166:169], v[38:41]
	v_mfma_f32_16x16x32_bf16 v[42:45], v[102:105], v[166:169], v[42:45]
	v_mfma_f32_16x16x32_bf16 v[46:49], v[78:81], v[166:169], v[46:49]
	v_mfma_f32_16x16x32_bf16 v[30:33], v[78:81], v[182:185], v[30:33]
	v_mfma_f32_16x16x32_bf16 v[26:29], v[102:105], v[182:185], v[26:29]
	v_mfma_f32_16x16x32_bf16 v[22:25], v[126:129], v[182:185], v[22:25]
	v_mfma_f32_16x16x32_bf16 v[18:21], v[142:145], v[182:185], v[18:21]
	v_mfma_f32_16x16x32_bf16 v[2:5], v[142:145], v[190:193], v[2:5]
	v_mfma_f32_16x16x32_bf16 v[6:9], v[126:129], v[190:193], v[6:9]
	v_mfma_f32_16x16x32_bf16 v[10:13], v[102:105], v[190:193], v[10:13]
	v_mfma_f32_16x16x32_bf16 v[14:17], v[78:81], v[190:193], v[14:17]
	v_mfma_f32_16x16x32_bf16 v[14:17], v[90:93], v[214:217], v[14:17]
	v_mfma_f32_16x16x32_bf16 v[10:13], v[114:117], v[214:217], v[10:13]
	v_mfma_f32_16x16x32_bf16 v[6:9], v[134:137], v[214:217], v[6:9]
	v_mfma_f32_16x16x32_bf16 v[2:5], v[154:157], v[214:217], v[2:5]
	v_mfma_f32_16x16x32_bf16 v[18:21], v[154:157], v[186:189], v[18:21]
	v_mfma_f32_16x16x32_bf16 v[22:25], v[134:137], v[186:189], v[22:25]
	v_mfma_f32_16x16x32_bf16 v[26:29], v[114:117], v[186:189], v[26:29]
	v_mfma_f32_16x16x32_bf16 v[30:33], v[90:93], v[186:189], v[30:33]
	v_mfma_f32_16x16x32_bf16 v[46:49], v[90:93], v[178:181], v[46:49]
	v_mfma_f32_16x16x32_bf16 v[42:45], v[114:117], v[178:181], v[42:45]
	v_mfma_f32_16x16x32_bf16 v[38:41], v[134:137], v[178:181], v[38:41]
	v_mfma_f32_16x16x32_bf16 v[34:37], v[154:157], v[178:181], v[34:37]
	v_mfma_f32_16x16x32_bf16 v[50:53], v[154:157], v[162:165], v[50:53]
	v_mfma_f32_16x16x32_bf16 v[54:57], v[134:137], v[162:165], v[54:57]
	v_mfma_f32_16x16x32_bf16 v[58:61], v[114:117], v[162:165], v[58:61]
	v_mfma_f32_16x16x32_bf16 v[62:65], v[90:93], v[162:165], v[62:65]
	s_setprio 0
	s_barrier
	s_add_i32 s18, 0, 0x18000
	s_add_i32 s19, 0, 0x1c000
	v_add_u32_e32 v114, s18, v1
	v_add_u32_e32 v154, s19, v1
	ds_read_b128 v[78:81], v114
	ds_read_b128 v[90:93], v114 offset:1024
	ds_read_b128 v[102:105], v114 offset:2048
	ds_read_b128 v[114:117], v114 offset:3072
	ds_read_b128 v[126:129], v154
	ds_read_b128 v[134:137], v154 offset:1024
	ds_read_b128 v[142:145], v154 offset:2048
	ds_read_b128 v[154:157], v154 offset:3072
	s_add_u32 s0, vcc_lo, 0x80000
	s_addc_u32 s1, vcc_hi, 0
	s_mov_b32 m0, s33
	v_lshl_add_u64 v[226:227], s[0:1], 0, v[194:195]
	ds_read_b128 v[158:161], v237 offset:32768
	ds_read_b128 v[162:165], v237 offset:33792
	ds_read_b128 v[166:169], v237 offset:34816
	ds_read_b128 v[178:181], v237 offset:35840
	ds_read_b128 v[182:185], v237 offset:36864
	ds_read_b128 v[186:189], v237 offset:37888
	ds_read_b128 v[190:193], v237 offset:38912
	ds_read_b128 v[214:217], v237 offset:39936
	global_load_lds_dwordx4 v[226:227], off
	v_lshl_add_u64 v[226:227], s[0:1], 0, v[204:205]
	s_mov_b32 m0, s43
	s_nop 0
	global_load_lds_dwordx4 v[226:227], off
	s_waitcnt vmcnt(8)
	s_waitcnt lgkmcnt(0)
	s_barrier
	s_setprio 1
	s_waitcnt lgkmcnt(0)
	v_mfma_f32_16x16x32_bf16 v[174:177], v[78:81], v[158:161], v[174:177]
	v_mfma_f32_16x16x32_bf16 v[170:173], v[102:105], v[158:161], v[170:173]
	v_mfma_f32_16x16x32_bf16 v[150:153], v[126:129], v[158:161], v[150:153]
	v_mfma_f32_16x16x32_bf16 v[146:149], v[142:145], v[158:161], v[146:149]
	v_mfma_f32_16x16x32_bf16 v[118:121], v[142:145], v[166:169], v[118:121]
	v_mfma_f32_16x16x32_bf16 v[122:125], v[126:129], v[166:169], v[122:125]
	v_mfma_f32_16x16x32_bf16 v[130:133], v[102:105], v[166:169], v[130:133]
	v_mfma_f32_16x16x32_bf16 v[138:141], v[78:81], v[166:169], v[138:141]
	v_mfma_f32_16x16x32_bf16 v[110:113], v[78:81], v[182:185], v[110:113]
	v_mfma_f32_16x16x32_bf16 v[106:109], v[102:105], v[182:185], v[106:109]
	v_mfma_f32_16x16x32_bf16 v[98:101], v[126:129], v[182:185], v[98:101]
	v_mfma_f32_16x16x32_bf16 v[94:97], v[142:145], v[182:185], v[94:97]
	v_mfma_f32_16x16x32_bf16 v[66:69], v[142:145], v[190:193], v[66:69]
	v_mfma_f32_16x16x32_bf16 v[74:77], v[126:129], v[190:193], v[74:77]
	v_mfma_f32_16x16x32_bf16 v[82:85], v[102:105], v[190:193], v[82:85]
	v_mfma_f32_16x16x32_bf16 v[86:89], v[78:81], v[190:193], v[86:89]
	v_mfma_f32_16x16x32_bf16 v[86:89], v[90:93], v[214:217], v[86:89]
	v_mfma_f32_16x16x32_bf16 v[82:85], v[114:117], v[214:217], v[82:85]
	v_mfma_f32_16x16x32_bf16 v[74:77], v[134:137], v[214:217], v[74:77]
	v_mfma_f32_16x16x32_bf16 v[66:69], v[154:157], v[214:217], v[66:69]
	v_mfma_f32_16x16x32_bf16 v[94:97], v[154:157], v[186:189], v[94:97]
	v_mfma_f32_16x16x32_bf16 v[98:101], v[134:137], v[186:189], v[98:101]
	v_mfma_f32_16x16x32_bf16 v[106:109], v[114:117], v[186:189], v[106:109]
	v_mfma_f32_16x16x32_bf16 v[110:113], v[90:93], v[186:189], v[110:113]
	v_mfma_f32_16x16x32_bf16 v[138:141], v[90:93], v[178:181], v[138:141]
	v_mfma_f32_16x16x32_bf16 v[130:133], v[114:117], v[178:181], v[130:133]
	v_mfma_f32_16x16x32_bf16 v[122:125], v[134:137], v[178:181], v[122:125]
	v_mfma_f32_16x16x32_bf16 v[118:121], v[154:157], v[178:181], v[118:121]
	v_mfma_f32_16x16x32_bf16 v[146:149], v[154:157], v[162:165], v[146:149]
	v_mfma_f32_16x16x32_bf16 v[150:153], v[134:137], v[162:165], v[150:153]
	v_mfma_f32_16x16x32_bf16 v[170:173], v[114:117], v[162:165], v[170:173]
	v_mfma_f32_16x16x32_bf16 v[174:177], v[90:93], v[162:165], v[174:177]
	s_setprio 0
	s_barrier
	s_add_i32 s0, s18, s28
	v_lshl_add_u64 v[218:219], v[218:219], 0, s[82:83]
	s_mov_b32 m0, s0
	ds_read_b128 v[158:161], v237 offset:49152
	ds_read_b128 v[162:165], v237 offset:50176
	ds_read_b128 v[166:169], v237 offset:51200
	ds_read_b128 v[178:181], v237 offset:52224
	ds_read_b128 v[182:185], v237 offset:53248
	ds_read_b128 v[186:189], v237 offset:54272
	ds_read_b128 v[190:193], v237 offset:55296
	ds_read_b128 v[214:217], v237 offset:56320
	global_load_lds_dwordx4 v[218:219], off
	s_add_i32 m0, s0, 0x2000
	s_add_u32 s0, s70, 0x80080
	v_lshl_add_u64 v[218:219], v[220:221], 0, s[82:83]
	s_addc_u32 s1, s71, 0
	s_add_i32 s18, s19, s28
	global_load_lds_dwordx4 v[218:219], off
	v_lshl_add_u64 v[218:219], s[0:1], 0, v[194:195]
	s_mov_b32 m0, s18
	s_nop 0
	global_load_lds_dwordx4 v[218:219], off
	v_lshl_add_u64 v[218:219], s[0:1], 0, v[204:205]
	s_add_i32 m0, s18, 0x2000
	s_nop 0
	global_load_lds_dwordx4 v[218:219], off
	v_lshl_add_u64 v[218:219], v[222:223], 0, s[82:83]
	s_mov_b32 m0, s68
	s_nop 0
	global_load_lds_dwordx4 v[218:219], off
	v_lshl_add_u64 v[218:219], v[224:225], 0, s[82:83]
	s_mov_b32 m0, s79
	s_nop 0
	global_load_lds_dwordx4 v[218:219], off
	s_waitcnt vmcnt(8)
	s_waitcnt lgkmcnt(0)
	s_barrier
	s_setprio 1
	s_waitcnt lgkmcnt(0)
	v_mfma_f32_16x16x32_bf16 v[62:65], v[78:81], v[158:161], v[62:65]
	v_mfma_f32_16x16x32_bf16 v[58:61], v[102:105], v[158:161], v[58:61]
	v_mfma_f32_16x16x32_bf16 v[54:57], v[126:129], v[158:161], v[54:57]
	v_mfma_f32_16x16x32_bf16 v[50:53], v[142:145], v[158:161], v[50:53]
	v_mfma_f32_16x16x32_bf16 v[34:37], v[142:145], v[166:169], v[34:37]
	v_mfma_f32_16x16x32_bf16 v[38:41], v[126:129], v[166:169], v[38:41]
	v_mfma_f32_16x16x32_bf16 v[42:45], v[102:105], v[166:169], v[42:45]
	v_mfma_f32_16x16x32_bf16 v[46:49], v[78:81], v[166:169], v[46:49]
	v_mfma_f32_16x16x32_bf16 v[30:33], v[78:81], v[182:185], v[30:33]
	v_mfma_f32_16x16x32_bf16 v[26:29], v[102:105], v[182:185], v[26:29]
	v_mfma_f32_16x16x32_bf16 v[22:25], v[126:129], v[182:185], v[22:25]
	v_mfma_f32_16x16x32_bf16 v[18:21], v[142:145], v[182:185], v[18:21]
	v_mfma_f32_16x16x32_bf16 v[2:5], v[142:145], v[190:193], v[2:5]
	v_mfma_f32_16x16x32_bf16 v[6:9], v[126:129], v[190:193], v[6:9]
	v_mfma_f32_16x16x32_bf16 v[10:13], v[102:105], v[190:193], v[10:13]
	v_mfma_f32_16x16x32_bf16 v[14:17], v[78:81], v[190:193], v[14:17]
	v_mfma_f32_16x16x32_bf16 v[14:17], v[90:93], v[214:217], v[14:17]
	v_mfma_f32_16x16x32_bf16 v[10:13], v[114:117], v[214:217], v[10:13]
	v_mfma_f32_16x16x32_bf16 v[6:9], v[134:137], v[214:217], v[6:9]
	v_mfma_f32_16x16x32_bf16 v[2:5], v[154:157], v[214:217], v[2:5]
	v_mfma_f32_16x16x32_bf16 v[18:21], v[154:157], v[186:189], v[18:21]
	v_mfma_f32_16x16x32_bf16 v[22:25], v[134:137], v[186:189], v[22:25]
	v_mfma_f32_16x16x32_bf16 v[26:29], v[114:117], v[186:189], v[26:29]
	v_mfma_f32_16x16x32_bf16 v[30:33], v[90:93], v[186:189], v[30:33]
	v_mfma_f32_16x16x32_bf16 v[46:49], v[90:93], v[178:181], v[46:49]
	v_mfma_f32_16x16x32_bf16 v[42:45], v[114:117], v[178:181], v[42:45]
	v_mfma_f32_16x16x32_bf16 v[38:41], v[134:137], v[178:181], v[38:41]
	v_mfma_f32_16x16x32_bf16 v[34:37], v[154:157], v[178:181], v[34:37]
	v_mfma_f32_16x16x32_bf16 v[50:53], v[154:157], v[162:165], v[50:53]
	v_mfma_f32_16x16x32_bf16 v[54:57], v[134:137], v[162:165], v[54:57]
	v_mfma_f32_16x16x32_bf16 v[58:61], v[114:117], v[162:165], v[58:61]
	v_mfma_f32_16x16x32_bf16 v[62:65], v[90:93], v[162:165], v[62:65]
	s_setprio 0
	s_barrier
	s_add_i32 s57, s57, 2
	s_add_u32 s51, s51, 0x100
	s_addc_u32 s53, s53, 0
	s_cmp_gt_u32 s57, 29
	s_mov_b64 s[76:77], s[90:91]
	s_cbranch_scc1 .LBB0_512

.LBB0_581:
	s_add_u32 s18, s62, 0xfff80080
	s_addc_u32 s19, s63, -1
	s_and_b64 s[0:1], s[64:65], exec
	s_cselect_b32 s71, s22, s19
	s_cselect_b32 s70, s23, s18
	s_cselect_b32 s65, s39, s58
	s_cselect_b32 s64, s47, s53
	s_add_i32 s0, 0, 0x10000
	v_add_u32_e32 v153, s0, v1
	s_add_i32 s18, 0, 0x14000
	ds_read_b128 v[144:147], v153
	ds_read_b128 v[148:151], v153 offset:1024
	ds_read_b128 v[154:157], v153 offset:2048
	ds_read_b128 v[158:161], v153 offset:3072
	v_add_u32_e32 v153, s18, v1
	ds_read_b128 v[162:165], v153
	ds_read_b128 v[166:169], v153 offset:1024
	ds_read_b128 v[170:173], v153 offset:2048
	ds_read_b128 v[174:177], v153 offset:3072
	v_lshl_add_u64 v[220:221], s[62:63], 0, v[136:137]
	s_add_i32 m0, s29, 0xc000
	ds_read_b128 v[178:181], v152
	ds_read_b128 v[182:185], v152 offset:1024
	ds_read_b128 v[186:189], v152 offset:2048
	ds_read_b128 v[190:193], v152 offset:3072
	ds_read_b128 v[204:207], v152 offset:4096
	ds_read_b128 v[208:211], v152 offset:5120
	ds_read_b128 v[212:215], v152 offset:6144
	ds_read_b128 v[216:219], v152 offset:7168
	global_load_lds_dwordx4 v[220:221], off
	v_lshl_add_u64 v[220:221], s[62:63], 0, v[138:139]
	s_add_i32 m0, s29, 0xe000
	s_nop 0
	global_load_lds_dwordx4 v[220:221], off
	s_waitcnt vmcnt(8)
	s_waitcnt lgkmcnt(0)
	s_barrier
	s_setprio 1
	s_waitcnt lgkmcnt(0)
	v_mfma_f32_16x16x32_bf16 v[126:129], v[144:147], v[178:181], v[126:129]
	v_mfma_f32_16x16x32_bf16 v[122:125], v[154:157], v[178:181], v[122:125]
	v_mfma_f32_16x16x32_bf16 v[118:121], v[162:165], v[178:181], v[118:121]
	v_mfma_f32_16x16x32_bf16 v[114:117], v[170:173], v[178:181], v[114:117]
	v_mfma_f32_16x16x32_bf16 v[98:101], v[170:173], v[186:189], v[98:101]
	v_mfma_f32_16x16x32_bf16 v[102:105], v[162:165], v[186:189], v[102:105]
	v_mfma_f32_16x16x32_bf16 v[106:109], v[154:157], v[186:189], v[106:109]
	v_mfma_f32_16x16x32_bf16 v[110:113], v[144:147], v[186:189], v[110:113]
	v_mfma_f32_16x16x32_bf16 v[94:97], v[144:147], v[204:207], v[94:97]
	v_mfma_f32_16x16x32_bf16 v[90:93], v[154:157], v[204:207], v[90:93]
	v_mfma_f32_16x16x32_bf16 v[86:89], v[162:165], v[204:207], v[86:89]
	v_mfma_f32_16x16x32_bf16 v[82:85], v[170:173], v[204:207], v[82:85]
	v_mfma_f32_16x16x32_bf16 v[66:69], v[170:173], v[212:215], v[66:69]
	v_mfma_f32_16x16x32_bf16 v[70:73], v[162:165], v[212:215], v[70:73]
	v_mfma_f32_16x16x32_bf16 v[74:77], v[154:157], v[212:215], v[74:77]
	v_mfma_f32_16x16x32_bf16 v[78:81], v[144:147], v[212:215], v[78:81]
	v_mfma_f32_16x16x32_bf16 v[78:81], v[148:151], v[216:219], v[78:81]
	v_mfma_f32_16x16x32_bf16 v[74:77], v[158:161], v[216:219], v[74:77]
	v_mfma_f32_16x16x32_bf16 v[70:73], v[166:169], v[216:219], v[70:73]
	v_mfma_f32_16x16x32_bf16 v[66:69], v[174:177], v[216:219], v[66:69]
	v_mfma_f32_16x16x32_bf16 v[82:85], v[174:177], v[208:211], v[82:85]
	v_mfma_f32_16x16x32_bf16 v[86:89], v[166:169], v[208:211], v[86:89]
	v_mfma_f32_16x16x32_bf16 v[90:93], v[158:161], v[208:211], v[90:93]
	v_mfma_f32_16x16x32_bf16 v[94:97], v[148:151], v[208:211], v[94:97]
	v_mfma_f32_16x16x32_bf16 v[110:113], v[148:151], v[190:193], v[110:113]
	v_mfma_f32_16x16x32_bf16 v[106:109], v[158:161], v[190:193], v[106:109]
	v_mfma_f32_16x16x32_bf16 v[102:105], v[166:169], v[190:193], v[102:105]
	v_mfma_f32_16x16x32_bf16 v[98:101], v[174:177], v[190:193], v[98:101]
	v_mfma_f32_16x16x32_bf16 v[114:117], v[174:177], v[182:185], v[114:117]
	v_mfma_f32_16x16x32_bf16 v[118:121], v[166:169], v[182:185], v[118:121]
	v_mfma_f32_16x16x32_bf16 v[122:125], v[158:161], v[182:185], v[122:125]
	v_mfma_f32_16x16x32_bf16 v[126:129], v[148:151], v[182:185], v[126:129]
	s_setprio 0
	s_barrier
	s_add_i32 s0, s0, s28
	v_lshl_add_u64 v[220:221], s[64:65], 0, v[194:195]
	s_mov_b32 m0, s0
	ds_read_b128 v[178:181], v152 offset:16384
	ds_read_b128 v[182:185], v152 offset:17408
	ds_read_b128 v[186:189], v152 offset:18432
	ds_read_b128 v[190:193], v152 offset:19456
	ds_read_b128 v[204:207], v152 offset:20480
	ds_read_b128 v[208:211], v152 offset:21504
	ds_read_b128 v[212:215], v152 offset:22528
	ds_read_b128 v[216:219], v152 offset:23552
	global_load_lds_dwordx4 v[220:221], off
	s_add_i32 m0, s0, 0x2000
	s_add_u32 s0, s64, 0x80000
	v_lshl_add_u64 v[222:223], s[64:65], 0, v[130:131]
	s_addc_u32 s1, s65, 0
	s_add_i32 s18, s18, s28
	global_load_lds_dwordx4 v[222:223], off
	v_lshl_add_u64 v[224:225], s[0:1], 0, v[194:195]
	s_mov_b32 m0, s18
	v_lshl_add_u64 v[226:227], s[70:71], 0, v[130:131]
	global_load_lds_dwordx4 v[224:225], off
	v_lshl_add_u64 v[224:225], s[0:1], 0, v[130:131]
	s_add_i32 m0, s18, 0x2000
	s_nop 0
	global_load_lds_dwordx4 v[224:225], off
	v_lshl_add_u64 v[224:225], s[70:71], 0, v[194:195]
	s_mov_b32 m0, s29
	s_nop 0
	global_load_lds_dwordx4 v[224:225], off
	s_mov_b32 m0, s31
	s_nop 0
	global_load_lds_dwordx4 v[226:227], off
	s_waitcnt vmcnt(8)
	s_waitcnt lgkmcnt(0)
	s_barrier
	s_setprio 1
	s_waitcnt lgkmcnt(0)
	v_mfma_f32_16x16x32_bf16 v[62:65], v[144:147], v[178:181], v[62:65]
	v_mfma_f32_16x16x32_bf16 v[58:61], v[154:157], v[178:181], v[58:61]
	v_mfma_f32_16x16x32_bf16 v[54:57], v[162:165], v[178:181], v[54:57]
	v_mfma_f32_16x16x32_bf16 v[50:53], v[170:173], v[178:181], v[50:53]
	v_mfma_f32_16x16x32_bf16 v[34:37], v[170:173], v[186:189], v[34:37]
	v_mfma_f32_16x16x32_bf16 v[38:41], v[162:165], v[186:189], v[38:41]
	v_mfma_f32_16x16x32_bf16 v[42:45], v[154:157], v[186:189], v[42:45]
	v_mfma_f32_16x16x32_bf16 v[46:49], v[144:147], v[186:189], v[46:49]
	v_mfma_f32_16x16x32_bf16 v[30:33], v[144:147], v[204:207], v[30:33]
	v_mfma_f32_16x16x32_bf16 v[26:29], v[154:157], v[204:207], v[26:29]
	v_mfma_f32_16x16x32_bf16 v[22:25], v[162:165], v[204:207], v[22:25]
	v_mfma_f32_16x16x32_bf16 v[18:21], v[170:173], v[204:207], v[18:21]
	v_mfma_f32_16x16x32_bf16 v[2:5], v[170:173], v[212:215], v[2:5]
	v_mfma_f32_16x16x32_bf16 v[6:9], v[162:165], v[212:215], v[6:9]
	v_mfma_f32_16x16x32_bf16 v[10:13], v[154:157], v[212:215], v[10:13]
	v_mfma_f32_16x16x32_bf16 v[14:17], v[144:147], v[212:215], v[14:17]
	v_mfma_f32_16x16x32_bf16 v[14:17], v[148:151], v[216:219], v[14:17]
	v_mfma_f32_16x16x32_bf16 v[10:13], v[158:161], v[216:219], v[10:13]
	v_mfma_f32_16x16x32_bf16 v[6:9], v[166:169], v[216:219], v[6:9]
	v_mfma_f32_16x16x32_bf16 v[2:5], v[174:177], v[216:219], v[2:5]
	v_mfma_f32_16x16x32_bf16 v[18:21], v[174:177], v[208:211], v[18:21]
	v_mfma_f32_16x16x32_bf16 v[22:25], v[166:169], v[208:211], v[22:25]
	v_mfma_f32_16x16x32_bf16 v[26:29], v[158:161], v[208:211], v[26:29]
	v_mfma_f32_16x16x32_bf16 v[30:33], v[148:151], v[208:211], v[30:33]
	v_mfma_f32_16x16x32_bf16 v[46:49], v[148:151], v[190:193], v[46:49]
	v_mfma_f32_16x16x32_bf16 v[42:45], v[158:161], v[190:193], v[42:45]
	v_mfma_f32_16x16x32_bf16 v[38:41], v[166:169], v[190:193], v[38:41]
	v_mfma_f32_16x16x32_bf16 v[34:37], v[174:177], v[190:193], v[34:37]
	v_mfma_f32_16x16x32_bf16 v[50:53], v[174:177], v[182:185], v[50:53]
	v_mfma_f32_16x16x32_bf16 v[54:57], v[166:169], v[182:185], v[54:57]
	v_mfma_f32_16x16x32_bf16 v[58:61], v[158:161], v[182:185], v[58:61]
	v_mfma_f32_16x16x32_bf16 v[62:65], v[148:151], v[182:185], v[62:65]
	s_setprio 0
	s_barrier
	s_add_i32 s18, 0, 0x18000
	v_add_u32_e32 v153, s18, v1
	s_add_i32 s19, 0, 0x1c000
	ds_read_b128 v[144:147], v153
	ds_read_b128 v[148:151], v153 offset:1024
	ds_read_b128 v[154:157], v153 offset:2048
	ds_read_b128 v[158:161], v153 offset:3072
	v_add_u32_e32 v153, s19, v1
	ds_read_b128 v[162:165], v153
	ds_read_b128 v[166:169], v153 offset:1024
	ds_read_b128 v[170:173], v153 offset:2048
	ds_read_b128 v[174:177], v153 offset:3072
	s_add_u32 s0, s70, 0x80000
	s_addc_u32 s1, s71, 0
	s_mov_b32 m0, s33
	v_lshl_add_u64 v[228:229], s[0:1], 0, v[194:195]
	ds_read_b128 v[178:181], v152 offset:32768
	ds_read_b128 v[182:185], v152 offset:33792
	ds_read_b128 v[186:189], v152 offset:34816
	ds_read_b128 v[190:193], v152 offset:35840
	ds_read_b128 v[204:207], v152 offset:36864
	ds_read_b128 v[208:211], v152 offset:37888
	ds_read_b128 v[212:215], v152 offset:38912
	ds_read_b128 v[216:219], v152 offset:39936
	global_load_lds_dwordx4 v[228:229], off
	v_lshl_add_u64 v[228:229], s[0:1], 0, v[130:131]
	s_mov_b32 m0, s40
	s_nop 0
	global_load_lds_dwordx4 v[228:229], off
	s_waitcnt vmcnt(8)
	s_waitcnt lgkmcnt(0)
	s_barrier
	s_setprio 1
	s_waitcnt lgkmcnt(0)
	v_mfma_f32_16x16x32_bf16 v[126:129], v[144:147], v[178:181], v[126:129]
	v_mfma_f32_16x16x32_bf16 v[122:125], v[154:157], v[178:181], v[122:125]
	v_mfma_f32_16x16x32_bf16 v[118:121], v[162:165], v[178:181], v[118:121]
	v_mfma_f32_16x16x32_bf16 v[114:117], v[170:173], v[178:181], v[114:117]
	v_mfma_f32_16x16x32_bf16 v[98:101], v[170:173], v[186:189], v[98:101]
	v_mfma_f32_16x16x32_bf16 v[102:105], v[162:165], v[186:189], v[102:105]
	v_mfma_f32_16x16x32_bf16 v[106:109], v[154:157], v[186:189], v[106:109]
	v_mfma_f32_16x16x32_bf16 v[110:113], v[144:147], v[186:189], v[110:113]
	v_mfma_f32_16x16x32_bf16 v[94:97], v[144:147], v[204:207], v[94:97]
	v_mfma_f32_16x16x32_bf16 v[90:93], v[154:157], v[204:207], v[90:93]
	v_mfma_f32_16x16x32_bf16 v[86:89], v[162:165], v[204:207], v[86:89]
	v_mfma_f32_16x16x32_bf16 v[82:85], v[170:173], v[204:207], v[82:85]
	v_mfma_f32_16x16x32_bf16 v[66:69], v[170:173], v[212:215], v[66:69]
	v_mfma_f32_16x16x32_bf16 v[70:73], v[162:165], v[212:215], v[70:73]
	v_mfma_f32_16x16x32_bf16 v[74:77], v[154:157], v[212:215], v[74:77]
	v_mfma_f32_16x16x32_bf16 v[78:81], v[144:147], v[212:215], v[78:81]
	v_mfma_f32_16x16x32_bf16 v[78:81], v[148:151], v[216:219], v[78:81]
	v_mfma_f32_16x16x32_bf16 v[74:77], v[158:161], v[216:219], v[74:77]
	v_mfma_f32_16x16x32_bf16 v[70:73], v[166:169], v[216:219], v[70:73]
	v_mfma_f32_16x16x32_bf16 v[66:69], v[174:177], v[216:219], v[66:69]
	v_mfma_f32_16x16x32_bf16 v[82:85], v[174:177], v[208:211], v[82:85]
	v_mfma_f32_16x16x32_bf16 v[86:89], v[166:169], v[208:211], v[86:89]
	v_mfma_f32_16x16x32_bf16 v[90:93], v[158:161], v[208:211], v[90:93]
	v_mfma_f32_16x16x32_bf16 v[94:97], v[148:151], v[208:211], v[94:97]
	v_mfma_f32_16x16x32_bf16 v[110:113], v[148:151], v[190:193], v[110:113]
	v_mfma_f32_16x16x32_bf16 v[106:109], v[158:161], v[190:193], v[106:109]
	v_mfma_f32_16x16x32_bf16 v[102:105], v[166:169], v[190:193], v[102:105]
	v_mfma_f32_16x16x32_bf16 v[98:101], v[174:177], v[190:193], v[98:101]
	v_mfma_f32_16x16x32_bf16 v[114:117], v[174:177], v[182:185], v[114:117]
	v_mfma_f32_16x16x32_bf16 v[118:121], v[166:169], v[182:185], v[118:121]
	v_mfma_f32_16x16x32_bf16 v[122:125], v[158:161], v[182:185], v[122:125]
	v_mfma_f32_16x16x32_bf16 v[126:129], v[148:151], v[182:185], v[126:129]
	s_setprio 0
	s_barrier
	s_add_i32 s0, s18, s28
	v_lshl_add_u64 v[220:221], v[220:221], 0, s[82:83]
	s_mov_b32 m0, s0
	ds_read_b128 v[178:181], v152 offset:49152
	ds_read_b128 v[182:185], v152 offset:50176
	ds_read_b128 v[186:189], v152 offset:51200
	ds_read_b128 v[190:193], v152 offset:52224
	ds_read_b128 v[204:207], v152 offset:53248
	ds_read_b128 v[208:211], v152 offset:54272
	ds_read_b128 v[212:215], v152 offset:55296
	ds_read_b128 v[216:219], v152 offset:56320
	global_load_lds_dwordx4 v[220:221], off
	s_add_i32 m0, s0, 0x2000
	s_add_u32 s0, s64, 0x80080
	v_lshl_add_u64 v[220:221], v[222:223], 0, s[82:83]
	s_addc_u32 s1, s65, 0
	s_add_i32 s18, s19, s28
	global_load_lds_dwordx4 v[220:221], off
	v_lshl_add_u64 v[220:221], s[0:1], 0, v[194:195]
	s_mov_b32 m0, s18
	s_nop 0
	global_load_lds_dwordx4 v[220:221], off
	v_lshl_add_u64 v[220:221], s[0:1], 0, v[130:131]
	s_add_i32 m0, s18, 0x2000
	s_nop 0
	global_load_lds_dwordx4 v[220:221], off
	v_lshl_add_u64 v[220:221], v[224:225], 0, s[82:83]
	s_mov_b32 m0, s54
	s_nop 0
	global_load_lds_dwordx4 v[220:221], off
	v_lshl_add_u64 v[220:221], v[226:227], 0, s[82:83]
	s_mov_b32 m0, s57
	s_nop 0
	global_load_lds_dwordx4 v[220:221], off
	s_waitcnt vmcnt(8)
	s_waitcnt lgkmcnt(0)
	s_barrier
	s_setprio 1
	s_waitcnt lgkmcnt(0)
	v_mfma_f32_16x16x32_bf16 v[62:65], v[144:147], v[178:181], v[62:65]
	v_mfma_f32_16x16x32_bf16 v[58:61], v[154:157], v[178:181], v[58:61]
	v_mfma_f32_16x16x32_bf16 v[54:57], v[162:165], v[178:181], v[54:57]
	v_mfma_f32_16x16x32_bf16 v[50:53], v[170:173], v[178:181], v[50:53]
	v_mfma_f32_16x16x32_bf16 v[34:37], v[170:173], v[186:189], v[34:37]
	v_mfma_f32_16x16x32_bf16 v[38:41], v[162:165], v[186:189], v[38:41]
	v_mfma_f32_16x16x32_bf16 v[42:45], v[154:157], v[186:189], v[42:45]
	v_mfma_f32_16x16x32_bf16 v[46:49], v[144:147], v[186:189], v[46:49]
	v_mfma_f32_16x16x32_bf16 v[30:33], v[144:147], v[204:207], v[30:33]
	v_mfma_f32_16x16x32_bf16 v[26:29], v[154:157], v[204:207], v[26:29]
	v_mfma_f32_16x16x32_bf16 v[22:25], v[162:165], v[204:207], v[22:25]
	v_mfma_f32_16x16x32_bf16 v[18:21], v[170:173], v[204:207], v[18:21]
	v_mfma_f32_16x16x32_bf16 v[2:5], v[170:173], v[212:215], v[2:5]
	v_mfma_f32_16x16x32_bf16 v[6:9], v[162:165], v[212:215], v[6:9]
	v_mfma_f32_16x16x32_bf16 v[10:13], v[154:157], v[212:215], v[10:13]
	v_mfma_f32_16x16x32_bf16 v[14:17], v[144:147], v[212:215], v[14:17]
	v_mfma_f32_16x16x32_bf16 v[14:17], v[148:151], v[216:219], v[14:17]
	v_mfma_f32_16x16x32_bf16 v[10:13], v[158:161], v[216:219], v[10:13]
	v_mfma_f32_16x16x32_bf16 v[6:9], v[166:169], v[216:219], v[6:9]
	v_mfma_f32_16x16x32_bf16 v[2:5], v[174:177], v[216:219], v[2:5]
	v_mfma_f32_16x16x32_bf16 v[18:21], v[174:177], v[208:211], v[18:21]
	v_mfma_f32_16x16x32_bf16 v[22:25], v[166:169], v[208:211], v[22:25]
	v_mfma_f32_16x16x32_bf16 v[26:29], v[158:161], v[208:211], v[26:29]
	v_mfma_f32_16x16x32_bf16 v[30:33], v[148:151], v[208:211], v[30:33]
	v_mfma_f32_16x16x32_bf16 v[46:49], v[148:151], v[190:193], v[46:49]
	v_mfma_f32_16x16x32_bf16 v[42:45], v[158:161], v[190:193], v[42:45]
	v_mfma_f32_16x16x32_bf16 v[38:41], v[166:169], v[190:193], v[38:41]
	v_mfma_f32_16x16x32_bf16 v[34:37], v[174:177], v[190:193], v[34:37]
	v_mfma_f32_16x16x32_bf16 v[50:53], v[174:177], v[182:185], v[50:53]
	v_mfma_f32_16x16x32_bf16 v[54:57], v[166:169], v[182:185], v[54:57]
	v_mfma_f32_16x16x32_bf16 v[58:61], v[158:161], v[182:185], v[58:61]
	v_mfma_f32_16x16x32_bf16 v[62:65], v[148:151], v[182:185], v[62:65]
	s_setprio 0
	s_barrier
	s_add_i32 s76, s76, 2
	s_add_u32 s62, s62, 0x100
	s_addc_u32 s63, s63, 0
	s_add_u32 s53, s53, 0x100
	s_addc_u32 s58, s58, 0
	s_cmp_gt_u32 s76, 29
	s_cbranch_scc1 .LBB0_584

.LBB0_645:
	s_add_u32 s64, s8, 0x100
	s_addc_u32 s65, s9, 0
	s_and_b64 s[0:1], s[70:71], exec
	s_cselect_b32 s77, s63, s65
	s_cselect_b32 s76, s62, s64
	s_cselect_b32 s71, s85, s23
	s_cselect_b32 s70, s84, s7
	s_add_i32 s0, 0, 0x10000
	s_add_i32 s18, 0, 0x14000
	v_add_u32_e32 v106, s0, v1
	v_add_u32_e32 v154, s18, v1
	ds_read_b128 v[70:73], v106
	ds_read_b128 v[82:85], v106 offset:1024
	ds_read_b128 v[94:97], v106 offset:2048
	ds_read_b128 v[106:109], v106 offset:3072
	ds_read_b128 v[118:121], v154
	ds_read_b128 v[130:133], v154 offset:1024
	ds_read_b128 v[142:145], v154 offset:2048
	ds_read_b128 v[154:157], v154 offset:3072
	v_lshl_add_u64 v[218:219], s[8:9], 0, v[206:207]
	s_add_i32 m0, s29, 0xc000
	ds_read_b128 v[158:161], v237
	ds_read_b128 v[170:173], v237 offset:1024
	ds_read_b128 v[174:177], v237 offset:2048
	ds_read_b128 v[178:181], v237 offset:3072
	ds_read_b128 v[182:185], v237 offset:4096
	ds_read_b128 v[186:189], v237 offset:5120
	ds_read_b128 v[210:213], v237 offset:6144
	ds_read_b128 v[214:217], v237 offset:7168
	global_load_lds_dwordx4 v[218:219], off
	v_lshl_add_u64 v[218:219], s[8:9], 0, v[208:209]
	s_add_i32 m0, s29, 0xe000
	s_nop 0
	global_load_lds_dwordx4 v[218:219], off
	s_waitcnt vmcnt(8)
	s_waitcnt lgkmcnt(0)
	s_barrier
	s_setprio 1
	s_waitcnt lgkmcnt(0)
	v_mfma_f32_16x16x32_bf16 v[166:169], v[70:73], v[158:161], v[166:169]
	v_mfma_f32_16x16x32_bf16 v[162:165], v[94:97], v[158:161], v[162:165]
	v_mfma_f32_16x16x32_bf16 v[150:153], v[118:121], v[158:161], v[150:153]
	v_mfma_f32_16x16x32_bf16 v[146:149], v[142:145], v[158:161], v[146:149]
	v_mfma_f32_16x16x32_bf16 v[122:125], v[142:145], v[174:177], v[122:125]
	v_mfma_f32_16x16x32_bf16 v[126:129], v[118:121], v[174:177], v[126:129]
	v_mfma_f32_16x16x32_bf16 v[134:137], v[94:97], v[174:177], v[134:137]
	v_mfma_f32_16x16x32_bf16 v[138:141], v[70:73], v[174:177], v[138:141]
	v_mfma_f32_16x16x32_bf16 v[114:117], v[70:73], v[182:185], v[114:117]
	v_mfma_f32_16x16x32_bf16 v[110:113], v[94:97], v[182:185], v[110:113]
	v_mfma_f32_16x16x32_bf16 v[102:105], v[118:121], v[182:185], v[102:105]
	v_mfma_f32_16x16x32_bf16 v[98:101], v[142:145], v[182:185], v[98:101]
	v_mfma_f32_16x16x32_bf16 v[74:77], v[142:145], v[210:213], v[74:77]
	v_mfma_f32_16x16x32_bf16 v[78:81], v[118:121], v[210:213], v[78:81]
	v_mfma_f32_16x16x32_bf16 v[86:89], v[94:97], v[210:213], v[86:89]
	v_mfma_f32_16x16x32_bf16 v[90:93], v[70:73], v[210:213], v[90:93]
	v_mfma_f32_16x16x32_bf16 v[90:93], v[82:85], v[214:217], v[90:93]
	v_mfma_f32_16x16x32_bf16 v[86:89], v[106:109], v[214:217], v[86:89]
	v_mfma_f32_16x16x32_bf16 v[78:81], v[130:133], v[214:217], v[78:81]
	v_mfma_f32_16x16x32_bf16 v[74:77], v[154:157], v[214:217], v[74:77]
	v_mfma_f32_16x16x32_bf16 v[98:101], v[154:157], v[186:189], v[98:101]
	v_mfma_f32_16x16x32_bf16 v[102:105], v[130:133], v[186:189], v[102:105]
	v_mfma_f32_16x16x32_bf16 v[110:113], v[106:109], v[186:189], v[110:113]
	v_mfma_f32_16x16x32_bf16 v[114:117], v[82:85], v[186:189], v[114:117]
	v_mfma_f32_16x16x32_bf16 v[138:141], v[82:85], v[178:181], v[138:141]
	v_mfma_f32_16x16x32_bf16 v[134:137], v[106:109], v[178:181], v[134:137]
	v_mfma_f32_16x16x32_bf16 v[126:129], v[130:133], v[178:181], v[126:129]
	v_mfma_f32_16x16x32_bf16 v[122:125], v[154:157], v[178:181], v[122:125]
	v_mfma_f32_16x16x32_bf16 v[146:149], v[154:157], v[170:173], v[146:149]
	v_mfma_f32_16x16x32_bf16 v[150:153], v[130:133], v[170:173], v[150:153]
	v_mfma_f32_16x16x32_bf16 v[162:165], v[106:109], v[170:173], v[162:165]
	v_mfma_f32_16x16x32_bf16 v[166:169], v[82:85], v[170:173], v[166:169]
	s_setprio 0
	s_barrier
	s_add_i32 s0, s0, s28
	v_lshl_add_u64 v[218:219], s[70:71], 0, v[192:193]
	s_mov_b32 m0, s0
	ds_read_b128 v[158:161], v237 offset:16384
	ds_read_b128 v[170:173], v237 offset:17408
	ds_read_b128 v[174:177], v237 offset:18432
	ds_read_b128 v[178:181], v237 offset:19456
	ds_read_b128 v[182:185], v237 offset:20480
	ds_read_b128 v[186:189], v237 offset:21504
	ds_read_b128 v[210:213], v237 offset:22528
	ds_read_b128 v[214:217], v237 offset:23552
	global_load_lds_dwordx4 v[218:219], off
	s_add_i32 m0, s0, 0x2000
	s_add_u32 s0, s70, 0x160000
	v_lshl_add_u64 v[220:221], s[70:71], 0, v[190:191]
	s_addc_u32 s1, s71, 0
	s_add_i32 s8, s18, s28
	global_load_lds_dwordx4 v[220:221], off
	v_lshl_add_u64 v[222:223], s[0:1], 0, v[192:193]
	s_mov_b32 m0, s8
	v_lshl_add_u64 v[224:225], s[76:77], 0, v[190:191]
	global_load_lds_dwordx4 v[222:223], off
	v_lshl_add_u64 v[222:223], s[0:1], 0, v[190:191]
	s_add_i32 m0, s8, 0x2000
	s_nop 0
	global_load_lds_dwordx4 v[222:223], off
	v_lshl_add_u64 v[222:223], s[76:77], 0, v[192:193]
	s_mov_b32 m0, s29
	s_nop 0
	global_load_lds_dwordx4 v[222:223], off
	s_mov_b32 m0, s31
	s_nop 0
	global_load_lds_dwordx4 v[224:225], off
	s_waitcnt vmcnt(8)
	s_waitcnt lgkmcnt(0)
	s_barrier
	s_setprio 1
	s_waitcnt lgkmcnt(0)
	v_mfma_f32_16x16x32_bf16 v[62:65], v[70:73], v[158:161], v[62:65]
	v_mfma_f32_16x16x32_bf16 v[58:61], v[94:97], v[158:161], v[58:61]
	v_mfma_f32_16x16x32_bf16 v[54:57], v[118:121], v[158:161], v[54:57]
	v_mfma_f32_16x16x32_bf16 v[50:53], v[142:145], v[158:161], v[50:53]
	v_mfma_f32_16x16x32_bf16 v[34:37], v[142:145], v[174:177], v[34:37]
	v_mfma_f32_16x16x32_bf16 v[38:41], v[118:121], v[174:177], v[38:41]
	v_mfma_f32_16x16x32_bf16 v[42:45], v[94:97], v[174:177], v[42:45]
	v_mfma_f32_16x16x32_bf16 v[46:49], v[70:73], v[174:177], v[46:49]
	v_mfma_f32_16x16x32_bf16 v[30:33], v[70:73], v[182:185], v[30:33]
	v_mfma_f32_16x16x32_bf16 v[26:29], v[94:97], v[182:185], v[26:29]
	v_mfma_f32_16x16x32_bf16 v[22:25], v[118:121], v[182:185], v[22:25]
	v_mfma_f32_16x16x32_bf16 v[18:21], v[142:145], v[182:185], v[18:21]
	v_mfma_f32_16x16x32_bf16 v[2:5], v[142:145], v[210:213], v[2:5]
	v_mfma_f32_16x16x32_bf16 v[6:9], v[118:121], v[210:213], v[6:9]
	v_mfma_f32_16x16x32_bf16 v[10:13], v[94:97], v[210:213], v[10:13]
	v_mfma_f32_16x16x32_bf16 v[14:17], v[70:73], v[210:213], v[14:17]
	v_mfma_f32_16x16x32_bf16 v[14:17], v[82:85], v[214:217], v[14:17]
	v_mfma_f32_16x16x32_bf16 v[10:13], v[106:109], v[214:217], v[10:13]
	v_mfma_f32_16x16x32_bf16 v[6:9], v[130:133], v[214:217], v[6:9]
	v_mfma_f32_16x16x32_bf16 v[2:5], v[154:157], v[214:217], v[2:5]
	v_mfma_f32_16x16x32_bf16 v[18:21], v[154:157], v[186:189], v[18:21]
	v_mfma_f32_16x16x32_bf16 v[22:25], v[130:133], v[186:189], v[22:25]
	v_mfma_f32_16x16x32_bf16 v[26:29], v[106:109], v[186:189], v[26:29]
	v_mfma_f32_16x16x32_bf16 v[30:33], v[82:85], v[186:189], v[30:33]
	v_mfma_f32_16x16x32_bf16 v[46:49], v[82:85], v[178:181], v[46:49]
	v_mfma_f32_16x16x32_bf16 v[42:45], v[106:109], v[178:181], v[42:45]
	v_mfma_f32_16x16x32_bf16 v[38:41], v[130:133], v[178:181], v[38:41]
	v_mfma_f32_16x16x32_bf16 v[34:37], v[154:157], v[178:181], v[34:37]
	v_mfma_f32_16x16x32_bf16 v[50:53], v[154:157], v[170:173], v[50:53]
	v_mfma_f32_16x16x32_bf16 v[54:57], v[130:133], v[170:173], v[54:57]
	v_mfma_f32_16x16x32_bf16 v[58:61], v[106:109], v[170:173], v[58:61]
	v_mfma_f32_16x16x32_bf16 v[62:65], v[82:85], v[170:173], v[62:65]
	s_setprio 0
	s_barrier
	s_add_i32 s8, 0, 0x18000
	s_add_i32 s9, 0, 0x1c000
	v_add_u32_e32 v106, s8, v1
	v_add_u32_e32 v154, s9, v1
	ds_read_b128 v[70:73], v106
	ds_read_b128 v[82:85], v106 offset:1024
	ds_read_b128 v[94:97], v106 offset:2048
	ds_read_b128 v[106:109], v106 offset:3072
	ds_read_b128 v[118:121], v154
	ds_read_b128 v[130:133], v154 offset:1024
	ds_read_b128 v[142:145], v154 offset:2048
	ds_read_b128 v[154:157], v154 offset:3072
	s_add_u32 s0, s76, 0x160000
	s_addc_u32 s1, s77, 0
	s_mov_b32 m0, s33
	v_lshl_add_u64 v[226:227], s[0:1], 0, v[192:193]
	ds_read_b128 v[158:161], v237 offset:32768
	ds_read_b128 v[170:173], v237 offset:33792
	ds_read_b128 v[174:177], v237 offset:34816
	ds_read_b128 v[178:181], v237 offset:35840
	ds_read_b128 v[182:185], v237 offset:36864
	ds_read_b128 v[186:189], v237 offset:37888
	ds_read_b128 v[210:213], v237 offset:38912
	ds_read_b128 v[214:217], v237 offset:39936
	global_load_lds_dwordx4 v[226:227], off
	v_lshl_add_u64 v[226:227], s[0:1], 0, v[190:191]
	s_mov_b32 m0, s43
	s_nop 0
	global_load_lds_dwordx4 v[226:227], off
	s_waitcnt vmcnt(8)
	s_waitcnt lgkmcnt(0)
	s_barrier
	s_setprio 1
	s_waitcnt lgkmcnt(0)
	v_mfma_f32_16x16x32_bf16 v[166:169], v[70:73], v[158:161], v[166:169]
	v_mfma_f32_16x16x32_bf16 v[162:165], v[94:97], v[158:161], v[162:165]
	v_mfma_f32_16x16x32_bf16 v[150:153], v[118:121], v[158:161], v[150:153]
	v_mfma_f32_16x16x32_bf16 v[146:149], v[142:145], v[158:161], v[146:149]
	v_mfma_f32_16x16x32_bf16 v[122:125], v[142:145], v[174:177], v[122:125]
	v_mfma_f32_16x16x32_bf16 v[126:129], v[118:121], v[174:177], v[126:129]
	v_mfma_f32_16x16x32_bf16 v[134:137], v[94:97], v[174:177], v[134:137]
	v_mfma_f32_16x16x32_bf16 v[138:141], v[70:73], v[174:177], v[138:141]
	v_mfma_f32_16x16x32_bf16 v[114:117], v[70:73], v[182:185], v[114:117]
	v_mfma_f32_16x16x32_bf16 v[110:113], v[94:97], v[182:185], v[110:113]
	v_mfma_f32_16x16x32_bf16 v[102:105], v[118:121], v[182:185], v[102:105]
	v_mfma_f32_16x16x32_bf16 v[98:101], v[142:145], v[182:185], v[98:101]
	v_mfma_f32_16x16x32_bf16 v[74:77], v[142:145], v[210:213], v[74:77]
	v_mfma_f32_16x16x32_bf16 v[78:81], v[118:121], v[210:213], v[78:81]
	v_mfma_f32_16x16x32_bf16 v[86:89], v[94:97], v[210:213], v[86:89]
	v_mfma_f32_16x16x32_bf16 v[90:93], v[70:73], v[210:213], v[90:93]
	v_mfma_f32_16x16x32_bf16 v[90:93], v[82:85], v[214:217], v[90:93]
	v_mfma_f32_16x16x32_bf16 v[86:89], v[106:109], v[214:217], v[86:89]
	v_mfma_f32_16x16x32_bf16 v[78:81], v[130:133], v[214:217], v[78:81]
	v_mfma_f32_16x16x32_bf16 v[74:77], v[154:157], v[214:217], v[74:77]
	v_mfma_f32_16x16x32_bf16 v[98:101], v[154:157], v[186:189], v[98:101]
	v_mfma_f32_16x16x32_bf16 v[102:105], v[130:133], v[186:189], v[102:105]
	v_mfma_f32_16x16x32_bf16 v[110:113], v[106:109], v[186:189], v[110:113]
	v_mfma_f32_16x16x32_bf16 v[114:117], v[82:85], v[186:189], v[114:117]
	v_mfma_f32_16x16x32_bf16 v[138:141], v[82:85], v[178:181], v[138:141]
	v_mfma_f32_16x16x32_bf16 v[134:137], v[106:109], v[178:181], v[134:137]
	v_mfma_f32_16x16x32_bf16 v[126:129], v[130:133], v[178:181], v[126:129]
	v_mfma_f32_16x16x32_bf16 v[122:125], v[154:157], v[178:181], v[122:125]
	v_mfma_f32_16x16x32_bf16 v[146:149], v[154:157], v[170:173], v[146:149]
	v_mfma_f32_16x16x32_bf16 v[150:153], v[130:133], v[170:173], v[150:153]
	v_mfma_f32_16x16x32_bf16 v[162:165], v[106:109], v[170:173], v[162:165]
	v_mfma_f32_16x16x32_bf16 v[166:169], v[82:85], v[170:173], v[166:169]
	s_setprio 0
	s_barrier
	s_add_i32 s0, s8, s28
	v_lshl_add_u64 v[218:219], v[218:219], 0, s[82:83]
	s_mov_b32 m0, s0
	ds_read_b128 v[158:161], v237 offset:49152
	ds_read_b128 v[170:173], v237 offset:50176
	ds_read_b128 v[174:177], v237 offset:51200
	ds_read_b128 v[178:181], v237 offset:52224
	ds_read_b128 v[182:185], v237 offset:53248
	ds_read_b128 v[186:189], v237 offset:54272
	ds_read_b128 v[210:213], v237 offset:55296
	ds_read_b128 v[214:217], v237 offset:56320
	global_load_lds_dwordx4 v[218:219], off
	s_add_i32 m0, s0, 0x2000
	s_add_u32 s0, s70, 0x160080
	v_lshl_add_u64 v[218:219], v[220:221], 0, s[82:83]
	s_addc_u32 s1, s71, 0
	s_add_i32 s8, s9, s28
	global_load_lds_dwordx4 v[218:219], off
	v_lshl_add_u64 v[218:219], s[0:1], 0, v[192:193]
	s_mov_b32 m0, s8
	s_nop 0
	global_load_lds_dwordx4 v[218:219], off
	v_lshl_add_u64 v[218:219], s[0:1], 0, v[190:191]
	s_add_i32 m0, s8, 0x2000
	s_nop 0
	global_load_lds_dwordx4 v[218:219], off
	v_lshl_add_u64 v[218:219], v[222:223], 0, s[82:83]
	s_mov_b32 m0, s68
	s_nop 0
	global_load_lds_dwordx4 v[218:219], off
	v_lshl_add_u64 v[218:219], v[224:225], 0, s[82:83]
	s_mov_b32 m0, s79
	s_nop 0
	global_load_lds_dwordx4 v[218:219], off
	s_waitcnt vmcnt(8)
	s_waitcnt lgkmcnt(0)
	s_barrier
	s_setprio 1
	s_waitcnt lgkmcnt(0)
	v_mfma_f32_16x16x32_bf16 v[62:65], v[70:73], v[158:161], v[62:65]
	v_mfma_f32_16x16x32_bf16 v[58:61], v[94:97], v[158:161], v[58:61]
	v_mfma_f32_16x16x32_bf16 v[54:57], v[118:121], v[158:161], v[54:57]
	v_mfma_f32_16x16x32_bf16 v[50:53], v[142:145], v[158:161], v[50:53]
	v_mfma_f32_16x16x32_bf16 v[34:37], v[142:145], v[174:177], v[34:37]
	v_mfma_f32_16x16x32_bf16 v[38:41], v[118:121], v[174:177], v[38:41]
	v_mfma_f32_16x16x32_bf16 v[42:45], v[94:97], v[174:177], v[42:45]
	v_mfma_f32_16x16x32_bf16 v[46:49], v[70:73], v[174:177], v[46:49]
	v_mfma_f32_16x16x32_bf16 v[30:33], v[70:73], v[182:185], v[30:33]
	v_mfma_f32_16x16x32_bf16 v[26:29], v[94:97], v[182:185], v[26:29]
	v_mfma_f32_16x16x32_bf16 v[22:25], v[118:121], v[182:185], v[22:25]
	v_mfma_f32_16x16x32_bf16 v[18:21], v[142:145], v[182:185], v[18:21]
	v_mfma_f32_16x16x32_bf16 v[2:5], v[142:145], v[210:213], v[2:5]
	v_mfma_f32_16x16x32_bf16 v[6:9], v[118:121], v[210:213], v[6:9]
	v_mfma_f32_16x16x32_bf16 v[10:13], v[94:97], v[210:213], v[10:13]
	v_mfma_f32_16x16x32_bf16 v[14:17], v[70:73], v[210:213], v[14:17]
	v_mfma_f32_16x16x32_bf16 v[14:17], v[82:85], v[214:217], v[14:17]
	v_mfma_f32_16x16x32_bf16 v[10:13], v[106:109], v[214:217], v[10:13]
	v_mfma_f32_16x16x32_bf16 v[6:9], v[130:133], v[214:217], v[6:9]
	v_mfma_f32_16x16x32_bf16 v[2:5], v[154:157], v[214:217], v[2:5]
	v_mfma_f32_16x16x32_bf16 v[18:21], v[154:157], v[186:189], v[18:21]
	v_mfma_f32_16x16x32_bf16 v[22:25], v[130:133], v[186:189], v[22:25]
	v_mfma_f32_16x16x32_bf16 v[26:29], v[106:109], v[186:189], v[26:29]
	v_mfma_f32_16x16x32_bf16 v[30:33], v[82:85], v[186:189], v[30:33]
	v_mfma_f32_16x16x32_bf16 v[46:49], v[82:85], v[178:181], v[46:49]
	v_mfma_f32_16x16x32_bf16 v[42:45], v[106:109], v[178:181], v[42:45]
	v_mfma_f32_16x16x32_bf16 v[38:41], v[130:133], v[178:181], v[38:41]
	v_mfma_f32_16x16x32_bf16 v[34:37], v[154:157], v[178:181], v[34:37]
	v_mfma_f32_16x16x32_bf16 v[50:53], v[154:157], v[170:173], v[50:53]
	v_mfma_f32_16x16x32_bf16 v[54:57], v[130:133], v[170:173], v[54:57]
	v_mfma_f32_16x16x32_bf16 v[58:61], v[106:109], v[170:173], v[58:61]
	v_mfma_f32_16x16x32_bf16 v[62:65], v[82:85], v[170:173], v[62:65]
	s_setprio 0
	s_barrier
	s_add_i32 s41, s41, 2
	s_add_u32 s7, s7, 0x100
	s_addc_u32 s23, s23, 0
	s_cmpk_gt_u32 s41, 0x55
	s_mov_b64 s[8:9], s[64:65]
	s_cbranch_scc1 .LBB0_648
